# retention ostore: per-thread address constants hoisted out of interval loop, straight-line LDS->global store (no /48, no 64-bit mads per trip)
# speedup vs baseline: 1.0027x; 1.0027x over previous
; template <int MODE>
; __device__ void scan_unit(int swave, const Params& p, int j, int b, int h, int dir, char* shm) {
;     ...
;     lg = log1pf(-exp2f((dir ? -5.5f : -5.0f) - (float)h));
;   }
;   const int vg = tid >> 4;
;   const float ret_ein = __expf(lg * (float)(ti + 1)), ret_eti = __expf(-lg * (float)(ti + 1)), ret_eout = __expf(lg * (float)(15 - ti)), ret_dd = __expf(lg * 16.f);
;   struct Raw { unsigned q, k, q2, k2; uint4 lr0, lr1; uint2 v; unsigned v30, v31, v32; float4 cs; };
;   auto tokof = [&](int c, int i) { int t = c * 16 + i; return dir ? (SEQ - 1 - t) : t; };
;   auto load_raw = [&](int c, Raw& R) {
;     const int tok = tokof(c, ti);
;     const bf16_t* row = P + (rowbase + tok) * LDP;
;     if (MODE == 0) {
;       R.q = *(const unsigned*)(row + E_GQ + h * 64 + dp); R.k = *(const unsigned*)(row + E_GK + h * 64 + dp);
;       const uint4* lrp = (const uint4*)(row + (dir ? E_GLB : E_GLF));
;       R.lr0 = lrp[0]; R.lr1 = lrp[1];
;       R.v = *(const uint2*)(row + E_GV + h * 128 + vg * 4);
;     } else if (MODE == 1) {
;       R.q = *(const unsigned*)(row + E_HQ + h * 64 + dp); R.k = *(const unsigned*)(row + (dir ? E_HZB : E_HZF) + h * 64 + dp);
;       R.v = *(const uint2*)(row + E_HI + h * 128 + vg * 4);
;     } else {
;       R.q = *(const unsigned*)(row + O_RQ + h * 128 + dp); R.q2 = *(const unsigned*)(row + O_RQ + h * 128 + 64 + dp);
;       R.k = *(const unsigned*)(row + O_RK + h * 128 + dp); R.k2 = *(const unsigned*)(row + O_RK + h * 128 + 64 + dp);
;       R.cs = *(const float4*)(rope + tok * 64 + dp);
;       const unsigned* vp = (const unsigned*)(row + O_RV + h * 192 + vg * 6);
;       R.v30 = vp[0]; R.v31 = vp[1]; R.v32 = vp[2];
;     }
.LBB0_562:
	s_and_b64 vcc, exec, s[0:1]
	s_cbranch_vccz .LBB0_627
	v_readlane_b32 s0, v246, 4
	v_readlane_b32 s12, v248, 8
	s_ashr_i32 s4, s0, 3
	s_bfe_u32 s8, s0, 0x20001
	s_and_b32 s5, s0, 1
	v_mov_b32_e32 v111, v147
	s_mov_b64 s[0:1], 0
	v_readlane_b32 s14, v248, 10
	v_readlane_b32 s15, v248, 11
	s_add_u32 s7, s14, s0
	s_addc_u32 s9, s15, s1
	s_cmp_eq_u32 s5, 0
	s_mov_b64 s[2:3], 0
	s_cselect_b64 s[0:1], -1, 0
	s_mov_b64 s[10:11], 0
	s_ashr_i32 s5, s4, 31
	v_cndmask_b32_e64 v0, v150, v151, s[0:1]
	v_cvt_f32_ubyte0_e32 v1, s8
	s_add_u32 s12, s14, s10
	v_sub_f32_e32 v0, v0, v1
	s_mov_b32 s10, 0xc2fc0000
	v_cmp_gt_f32_e32 vcc, s10, v0
	v_readlane_b32 s13, v248, 9
	s_addc_u32 s13, s15, s11
	v_cndmask_b32_e32 v1, 0, v152, vcc
	v_add_f32_e32 v0, v0, v1
	v_exp_f32_e32 v0, v0
	s_and_b64 s[10:11], vcc, exec
	s_cselect_b32 s10, 0xffffffc0, 0
	v_ashrrev_i32_e32 v2, 3, v111
	v_ldexp_f32 v36, v0, s10
	s_waitcnt vmcnt(0)
	v_sub_f32_e32 v4, 1.0, v36
	v_add_f32_e32 v0, -1.0, v4
	v_sub_f32_e32 v1, v0, v4
	v_add_f32_e32 v1, 1.0, v1
	v_sub_f32_e64 v0, -v36, v0
	v_add_f32_e32 v5, v0, v1
	v_frexp_mant_f32_e32 v6, v4
	v_cvt_f64_f32_e32 v[0:1], v4
	s_mov_b32 s10, 0x3f2aaaab
	v_frexp_exp_i32_f64_e32 v0, v[0:1]
	v_cmp_gt_f32_e32 vcc, s10, v6
	s_mov_b32 s10, 0x3f317218
	s_add_u32 s44, s7, 0xc000000
	s_waitcnt vmcnt(0)
	v_subbrev_co_u32_e32 v10, vcc, 0, v0, vcc
	v_sub_u32_e32 v0, 0, v10
	v_ldexp_f32 v1, v4, v0
	v_add_f32_e32 v4, -1.0, v1
	v_add_f32_e32 v6, 1.0, v1
	v_ldexp_f32 v0, v5, v0
	v_add_f32_e32 v5, 1.0, v4
	v_add_f32_e32 v7, -1.0, v6
	v_sub_f32_e32 v5, v1, v5
	v_sub_f32_e32 v1, v1, v7
	v_add_f32_e32 v5, v0, v5
	v_add_f32_e32 v0, v0, v1
	v_add_f32_e32 v11, v6, v0
	v_rcp_f32_e32 v13, v11
	v_sub_f32_e32 v1, v11, v6
	v_sub_f32_e32 v12, v0, v1
	v_add_f32_e32 v1, v4, v5
	v_mul_f32_e32 v15, v1, v13
	v_sub_f32_e32 v0, v1, v4
	v_mul_f32_e32 v4, v11, v15
	v_fma_f32 v6, v15, v11, -v4
	v_fmac_f32_e32 v6, v15, v12
	v_sub_f32_e32 v14, v5, v0
	v_add_f32_e32 v0, v4, v6
	v_sub_f32_e32 v5, v1, v0
	v_pk_add_f32 v[8:9], v[0:1], v[4:5] neg_lo:[0,1] neg_hi:[0,1]
	v_mov_b32_e32 v7, v0
	v_pk_add_f32 v[0:1], v[8:9], v[6:7] neg_lo:[0,1] neg_hi:[0,1]
	s_movk_i32 s7, 0x7ff
	v_add_f32_e32 v1, v14, v1
	v_add_f32_e32 v0, v0, v1
	v_add_f32_e32 v1, v5, v0
	v_mul_f32_e32 v14, v13, v1
	v_mul_f32_e32 v4, v11, v14
	v_fma_f32 v6, v14, v11, -v4
	v_fmac_f32_e32 v6, v14, v12
	v_sub_f32_e32 v5, v5, v1
	v_add_f32_e32 v11, v0, v5
	v_add_f32_e32 v0, v4, v6
	v_sub_f32_e32 v5, v1, v0
	v_pk_add_f32 v[8:9], v[0:1], v[4:5] neg_lo:[0,1] neg_hi:[0,1]
	v_mov_b32_e32 v7, v0
	v_pk_add_f32 v[0:1], v[8:9], v[6:7] neg_lo:[0,1] neg_hi:[0,1]
	v_and_b32_e32 v116, 15, v111
	v_add_f32_e32 v1, v11, v1
	v_add_f32_e32 v0, v0, v1
	v_add_f32_e32 v1, v15, v14
	v_add_f32_e32 v0, v5, v0
	v_sub_f32_e32 v4, v1, v15
	v_mul_f32_e32 v0, v13, v0
	v_sub_f32_e32 v4, v14, v4
	v_add_f32_e32 v4, v4, v0
	v_add_f32_e32 v6, v1, v4
	v_mul_f32_e32 v7, v6, v6
	v_fmamk_f32 v0, v7, 0x3e9b6dac, v148
	v_fmaak_f32 v135, v7, v0, 0x3f2aaada
	v_cvt_f32_i32_e32 v0, v10
	v_sub_f32_e32 v1, v6, v1
	v_sub_f32_e32 v1, v4, v1
	v_ldexp_f32 v8, v1, 1
	v_mul_f32_e32 v1, v6, v7
	v_ldexp_f32 v5, v6, 1
	v_pk_mul_f32 v[6:7], v[0:1], v[134:135]
	v_and_b32_e32 v12, -2, v2
	v_fma_f32 v4, v0, s10, -v6
	v_fmac_f32_e32 v4, 0xb102e308, v0
	v_pk_add_f32 v[0:1], v[6:7], v[4:5]
	v_bitop3_b32 v2, v111, s7, 15 bitop3:0x6c
	v_sub_f32_e32 v5, v1, v5
	v_sub_f32_e32 v5, v7, v5
	s_addc_u32 s45, s9, 0
	s_lshl_b64 s[18:19], s[4:5], 11
	v_cndmask_b32_e64 v2, v2, v116, s[0:1]
	v_add_f32_e32 v17, v8, v5
	v_or_b32_e32 v5, s18, v2
	v_mov_b64_e32 v[18:19], s[44:45]
	s_add_u32 s4, s12, 0x1eb9c000
	v_mad_u64_u32 v[8:9], s[10:11], v5, s55, v[18:19]
	s_addc_u32 s5, s13, 0
	v_ashrrev_i32_e32 v11, 4, v111
	v_mad_i32_i24 v9, s19, v155, v9
	s_lshl_b32 s94, s8, 8
	v_ashrrev_i32_e32 v13, 31, v12
	s_mul_i32 s6, s8, 0xc0
	v_lshl_add_u64 v[14:15], v[8:9], 0, s[94:95]
	v_lshlrev_b64 v[118:119], 1, v[12:13]
	v_mul_lo_u32 v22, v11, 6
	v_lshl_add_u64 v[14:15], v[14:15], 0, v[118:119]
	v_lshlrev_b32_e32 v2, 9, v2
	s_lshl_b32 s46, s6, 1
	s_mov_b32 s47, s95
	v_ashrrev_i32_e32 v23, 31, v22
	s_barrier
	global_load_dword v37, v[14:15], off
	global_load_dword v38, v[14:15], off offset:128
	global_load_dword v39, v[14:15], off offset:1024
	global_load_dword v40, v[14:15], off offset:1152
	v_lshl_add_u64 v[20:21], s[4:5], 0, v[2:3]
	v_lshlrev_b64 v[14:15], 3, v[12:13]
	v_lshl_add_u64 v[8:9], v[8:9], 0, s[46:47]
	v_lshlrev_b64 v[122:123], 1, v[22:23]
	v_mov_b32_e32 v16, v6
	v_lshl_add_u64 v[20:21], v[20:21], 0, v[14:15]
	v_lshl_add_u64 v[8:9], v[8:9], 0, v[122:123]
	v_pk_add_f32 v[6:7], v[0:1], v[6:7] neg_lo:[0,1] neg_hi:[0,1]
	global_load_dwordx3 v[8:10], v[8:9], off offset:2048
	s_nop 0
	global_load_dwordx4 v[26:29], v[20:21], off
	v_pk_add_f32 v[20:21], v[0:1], v[16:17]
	v_mov_b32_e32 v5, v0
	v_mov_b32_e32 v7, v21
	v_pk_add_f32 v[30:31], v[4:5], v[6:7] neg_lo:[0,1] neg_hi:[0,1]
	v_pk_add_f32 v[4:5], v[4:5], v[6:7]
	v_mov_b32_e32 v24, v1
	v_pk_add_f32 v[6:7], v[4:5], v[0:1] op_sel:[1,0] op_sel_hi:[0,1] neg_lo:[0,1] neg_hi:[0,1]
	v_pk_add_f32 v[22:23], v[20:21], v[6:7] op_sel_hi:[1,0] neg_lo:[0,1] neg_hi:[0,1]
	v_mov_b32_e32 v20, v21
	v_mov_b32_e32 v21, v5
	v_mov_b32_e32 v25, v6
	v_pk_add_f32 v[6:7], v[20:21], v[24:25] neg_lo:[0,1] neg_hi:[0,1]
	v_mov_b32_e32 v16, v17
	v_mov_b32_e32 v17, v0
	v_pk_add_f32 v[0:1], v[16:17], v[6:7] neg_lo:[0,1] neg_hi:[0,1]
	v_mov_b32_e32 v22, v30
	v_pk_add_f32 v[16:17], v[22:23], v[0:1]
	v_mov_b32_e32 v31, v5
	v_pk_add_f32 v[6:7], v[16:17], v[16:17] op_sel:[0,1] op_sel_hi:[1,0]
	s_movk_i32 s6, 0x7ef
	v_pk_add_f32 v[20:21], v[4:5], v[6:7] op_sel:[1,0] op_sel_hi:[0,1]
; __device__ __forceinline__ unsigned pk2(float lo, float hi) { f32x2_t v = {lo, hi}; bf16x2_t b = __builtin_convertvector(v, bf16x2_t); return __builtin_bit_cast(unsigned, b); }
; __device__ __forceinline__ bf16_t f2bf(float f) { return (bf16_t)(pk2(f, 0.f) & 0xffffu); }
; __device__ __forceinline__ float lo_bf(unsigned u) { return __uint_as_float(u << 16); }
; __device__ __forceinline__ float hi_bf(unsigned u) { return __uint_as_float(u & 0xffff0000u); }
; template <int MODE>
; __device__ void scan_unit(int swave, const Params& p, int j, int b, int h, int dir, char* shm) {
;     ...
;   const float ret_ein = __expf(lg * (float)(ti + 1)), ret_eti = __expf(-lg * (float)(ti + 1)), ret_eout = __expf(lg * (float)(15 - ti)), ret_dd = __expf(lg * 16.f);
;     ...
;       const float KSC = 0.08838834764831845f;
;       const float qx0 = lo_bf(R.q), qx1 = hi_bf(R.q), qy0 = lo_bf(R.q2), qy1 = hi_bf(R.q2);
;       const float kx0 = lo_bf(R.k) * KSC, kx1 = hi_bf(R.k) * KSC, ky0 = lo_bf(R.k2) * KSC, ky1 = hi_bf(R.k2) * KSC;
;       const float c0 = R.cs.x, sn0 = R.cs.y, c1 = R.cs.z, sn1 = R.cs.w;
;       const float qa0 = qx0 * c0 - qy0 * sn0, qb0 = qx0 * sn0 + qy0 * c0, qa1 = qx1 * c1 - qy1 * sn1, qb1 = qx1 * sn1 + qy1 * c1;
;       const float ka0 = kx0 * c0 - ky0 * sn0, kb0 = kx0 * sn0 + ky0 * c0, ka1 = kx1 * c1 - ky1 * sn1, kb1 = kx1 * sn1 + ky1 * c1;
;       const float ein = ret_ein, eti = ret_eti, eout = ret_eout;
;       *(unsigned*)(qin + ti * QS + dp) = pk2(qa0 * ein, qa1 * ein); *(unsigned*)(qin + ti * QS + 64 + dp) = pk2(qb0 * ein, qb1 * ein);
;       *(unsigned*)(ktil + ti * QS + dp) = pk2(ka0 * eti, ka1 * eti); *(unsigned*)(ktil + ti * QS + 64 + dp) = pk2(kb0 * eti, kb1 * eti);
;       koutT[dp * 16 + ti] = f2bf(ka0 * eout); koutT[(dp + 1) * 16 + ti] = f2bf(ka1 * eout);
;       koutT[(64 + dp) * 16 + ti] = f2bf(kb0 * eout); koutT[(65 + dp) * 16 + ti] = f2bf(kb1 * eout);
;       if (ti == 0) { const float dd = ret_dd; *(float2*)(dec + dp) = make_float2(dd, dd); *(float2*)(dec + 64 + dp) = make_float2(dd, dd); }
;       const int c6 = vg * 6;
;       vT[(c6 + 0) * VS + ti] = (bf16_t)(R.v30 & 0xffff); vT[(c6 + 1) * VS + ti] = (bf16_t)(R.v30 >> 16);
;       vT[(c6 + 2) * VS + ti] = (bf16_t)(R.v31 & 0xffff); vT[(c6 + 3) * VS + ti] = (bf16_t)(R.v31 >> 16);
;       vT[(c6 + 4) * VS + ti] = (bf16_t)(R.v32 & 0xffff); vT[(c6 + 5) * VS + ti] = (bf16_t)(R.v32 >> 16);
	v_mov_b32_e32 v17, v20
	v_pk_add_f32 v[32:33], v[16:17], v[30:31] neg_lo:[0,1] neg_hi:[0,1]
	v_mov_b32_e32 v1, v6
	v_pk_add_f32 v[34:35], v[0:1], v[32:33] neg_lo:[0,1] neg_hi:[0,1]
	v_or_b32_e32 v13, 16, v116
	v_bitop3_b32 v0, v111, s6, 15 bitop3:0x6c
	v_cndmask_b32_e64 v2, v0, v13, s[0:1]
	v_or_b32_e32 v0, s18, v2
	v_mad_u64_u32 v[0:1], s[6:7], v0, s55, v[18:19]
	v_mad_i32_i24 v1, s19, v155, v1
	v_lshl_add_u64 v[4:5], v[0:1], 0, s[94:95]
	v_lshl_add_u64 v[4:5], v[4:5], 0, v[118:119]
	v_lshlrev_b32_e32 v2, 9, v2
	global_load_dword v24, v[4:5], off
	global_load_dword v23, v[4:5], off offset:128
	global_load_dword v22, v[4:5], off offset:1024
	global_load_dword v21, v[4:5], off offset:1152
	v_lshl_add_u64 v[4:5], s[4:5], 0, v[2:3]
	v_lshl_add_u64 v[0:1], v[0:1], 0, s[46:47]
	v_lshl_add_u64 v[4:5], v[4:5], 0, v[14:15]
	v_lshl_add_u64 v[0:1], v[0:1], 0, v[122:123]
	global_load_dwordx4 v[4:7], v[4:5], off
	s_nop 0
	global_load_dwordx3 v[0:2], v[0:1], off offset:2048
	v_sub_f32_e32 v16, v16, v32
	v_sub_f32_e32 v16, v30, v16
	v_add_f32_e32 v16, v34, v16
	v_add_f32_e32 v16, v16, v35
	v_add_f32_e32 v16, v20, v16
	v_cmp_nlt_f32_e32 vcc, 1.0, v36
	s_mov_b32 s6, 0x33800000
	v_add_u32_e32 v17, 1, v116
	v_cndmask_b32_e32 v16, v153, v16, vcc
	v_cmp_neq_f32_e32 vcc, 1.0, v36
	v_cvt_f32_ubyte0_e32 v17, v17
	v_bitop3_b32 v19, v111, 15, v111 bitop3:0xc
	v_cndmask_b32_e32 v16, v154, v16, vcc
	v_cmp_gt_f32_e32 vcc, s6, v36
	v_cvt_f32_ubyte0_e32 v19, v19
	s_mov_b32 s6, 0x3db504f3
	v_cndmask_b32_e64 v16, v16, -v36, vcc
	v_mul_f32_e32 v18, v16, v17
	v_mul_f32_e32 v18, 0x3fb8aa3b, v18
	v_mul_f32_e64 v17, -v16, v17
	v_mul_f32_e32 v19, v16, v19
	v_mul_f32_e32 v16, 0x41800000, v16
	v_mul_f32_e32 v17, 0x3fb8aa3b, v17
	v_mul_f32_e32 v16, 0x3fb8aa3b, v16
	v_exp_f32_e32 v124, v18
	v_mul_f32_e32 v19, 0x3fb8aa3b, v19
	v_exp_f32_e32 v126, v17
	v_exp_f32_e32 v128, v16
	s_waitcnt vmcnt(0)
	v_lshlrev_b32_e32 v16, 16, v37
	v_and_b32_e32 v17, 0xffff0000, v37
	s_waitcnt vmcnt(10)
	v_lshlrev_b32_e32 v30, 16, v38
	v_and_b32_e32 v31, 0xffff0000, v38
	v_exp_f32_e32 v117, v19
	s_waitcnt vmcnt(8)
	v_lshlrev_b32_e32 v34, 16, v40
	v_and_b32_e32 v35, 0xffff0000, v40
	v_lshlrev_b32_e32 v32, 16, v39
	v_and_b32_e32 v33, 0xffff0000, v39
	v_cmp_ne_u32_e32 vcc, 0, v116
	s_waitcnt vmcnt(6)
	v_mov_b32_e32 v37, v28
	v_mov_b32_e32 v28, v27
	v_mov_b32_e32 v36, v26
	v_pk_mul_f32 v[18:19], v[28:29], v[30:31]
	v_pk_mul_f32 v[26:27], v[34:35], s[6:7] op_sel_hi:[1,0]
	v_pk_fma_f32 v[18:19], v[36:37], v[16:17], v[18:19] neg_lo:[0,0,1] neg_hi:[0,0,1]
	v_pk_mul_f32 v[16:17], v[28:29], v[16:17]
	v_pk_mul_f32 v[18:19], v[124:125], v[18:19] op_sel_hi:[0,1]
	v_cvt_pk_bf16_f32 v20, v18, v19
	v_mul_u32_u24_e32 v19, 0x88, v116
	v_pk_fma_f32 v[16:17], v[36:37], v[30:31], v[16:17]
	v_lshl_add_u32 v18, v19, 1, 0
	v_pk_mul_f32 v[16:17], v[124:125], v[16:17] op_sel_hi:[0,1]
	v_lshl_add_u32 v121, v12, 1, v18
	v_cvt_pk_bf16_f32 v16, v16, v17
	ds_write2_b32 v121, v20, v16 offset1:32
	v_pk_mul_f32 v[16:17], v[32:33], s[6:7] op_sel_hi:[1,0]
	v_pk_mul_f32 v[30:31], v[28:29], v[26:27]
	v_add_u32_e32 v135, 0x1000, v121
	v_pk_fma_f32 v[30:31], v[36:37], v[16:17], v[30:31] neg_lo:[0,0,1] neg_hi:[0,0,1]
	v_pk_mul_f32 v[16:17], v[16:17], v[28:29]
	v_pk_mul_f32 v[32:33], v[126:127], v[30:31] op_sel_hi:[0,1]
	v_pk_fma_f32 v[16:17], v[26:27], v[36:37], v[16:17]
	v_cvt_pk_bf16_f32 v20, v32, v33
	v_pk_mul_f32 v[26:27], v[126:127], v[16:17] op_sel_hi:[0,1]
	v_cvt_pk_bf16_f32 v25, v26, v27
	ds_write2_b32 v135, v20, v25 offset0:64 offset1:96
	v_mul_f32_e32 v20, v117, v30
	v_cvt_pk_bf16_f32 v25, v20, s0
	v_lshl_or_b32 v20, v12, 4, v116
	v_lshl_add_u32 v136, v20, 1, 0
	v_mul_f32_e32 v16, v117, v16
	ds_write_b16 v136, v25 offset:8704
	v_mul_f32_e32 v25, v117, v31
	v_cvt_pk_bf16_f32 v16, v16, s0
	v_cvt_pk_bf16_f32 v25, v25, s0
	ds_write_b16 v136, v16 offset:10752
	v_mul_f32_e32 v16, v117, v17
	ds_write_b16 v136, v25 offset:8736
	v_cvt_pk_bf16_f32 v16, v16, s0
	v_cmp_eq_u32_e64 s[16:17], 0, v116
	v_lshl_add_u32 v25, v12, 2, 0
	ds_write_b16 v136, v16 offset:10784
	s_and_saveexec_b64 s[6:7], s[16:17]
	v_mov_b32_e32 v129, v128
	v_add_u32_e32 v16, 0x5000, v25
	ds_write2_b64 v16, v[128:129], v[128:129] offset1:32
	s_or_b64 exec, exec, s[6:7]
	s_movk_i32 s6, 0x78
	v_mad_u64_u32 v[16:17], s[6:7], v11, s6, v[116:117]
	v_lshl_add_u32 v137, v16, 1, 0
	ds_write_b16 v137, v8 offset:12800
	ds_write_b16_d16_hi v137, v8 offset:12840
	ds_write_b16 v137, v9 offset:12880
	ds_write_b16_d16_hi v137, v9 offset:12920
	ds_write_b16 v137, v10 offset:12960
	ds_write_b16_d16_hi v137, v10 offset:13000
	s_waitcnt vmcnt(0)
	v_lshlrev_b32_e32 v10, 16, v23
	v_and_b32_e32 v11, 0xffff0000, v23
	s_waitcnt vmcnt(1)
; __device__ __forceinline__ unsigned pk2(float lo, float hi) { f32x2_t v = {lo, hi}; bf16x2_t b = __builtin_convertvector(v, bf16x2_t); return __builtin_bit_cast(unsigned, b); }
; __device__ __forceinline__ bf16_t f2bf(float f) { return (bf16_t)(pk2(f, 0.f) & 0xffffu); }
; __device__ __forceinline__ float lo_bf(unsigned u) { return __uint_as_float(u << 16); }
; __device__ __forceinline__ float hi_bf(unsigned u) { return __uint_as_float(u & 0xffff0000u); }
; template <int MODE>
; __device__ void scan_unit(int swave, const Params& p, int j, int b, int h, int dir, char* shm) {
;     ...
;       const float KSC = 0.08838834764831845f;
;       const float qx0 = lo_bf(R.q), qx1 = hi_bf(R.q), qy0 = lo_bf(R.q2), qy1 = hi_bf(R.q2);
;       const float kx0 = lo_bf(R.k) * KSC, kx1 = hi_bf(R.k) * KSC, ky0 = lo_bf(R.k2) * KSC, ky1 = hi_bf(R.k2) * KSC;
;       const float c0 = R.cs.x, sn0 = R.cs.y, c1 = R.cs.z, sn1 = R.cs.w;
;       const float qa0 = qx0 * c0 - qy0 * sn0, qb0 = qx0 * sn0 + qy0 * c0, qa1 = qx1 * c1 - qy1 * sn1, qb1 = qx1 * sn1 + qy1 * c1;
;       const float ka0 = kx0 * c0 - ky0 * sn0, kb0 = kx0 * sn0 + ky0 * c0, ka1 = kx1 * c1 - ky1 * sn1, kb1 = kx1 * sn1 + ky1 * c1;
;       const float ein = ret_ein, eti = ret_eti, eout = ret_eout;
;       *(unsigned*)(qin + ti * QS + dp) = pk2(qa0 * ein, qa1 * ein); *(unsigned*)(qin + ti * QS + 64 + dp) = pk2(qb0 * ein, qb1 * ein);
;       *(unsigned*)(ktil + ti * QS + dp) = pk2(ka0 * eti, ka1 * eti); *(unsigned*)(ktil + ti * QS + 64 + dp) = pk2(kb0 * eti, kb1 * eti);
;       koutT[dp * 16 + ti] = f2bf(ka0 * eout); koutT[(dp + 1) * 16 + ti] = f2bf(ka1 * eout);
;       koutT[(64 + dp) * 16 + ti] = f2bf(kb0 * eout); koutT[(65 + dp) * 16 + ti] = f2bf(kb1 * eout);
;       if (ti == 0) { const float dd = ret_dd; *(float2*)(dec + dp) = make_float2(dd, dd); *(float2*)(dec + 64 + dp) = make_float2(dd, dd); }
;       const int c6 = vg * 6;
;       vT[(c6 + 0) * VS + ti] = (bf16_t)(R.v30 & 0xffff); vT[(c6 + 1) * VS + ti] = (bf16_t)(R.v30 >> 16);
;       vT[(c6 + 2) * VS + ti] = (bf16_t)(R.v31 & 0xffff); vT[(c6 + 3) * VS + ti] = (bf16_t)(R.v31 >> 16);
;       vT[(c6 + 4) * VS + ti] = (bf16_t)(R.v32 & 0xffff); vT[(c6 + 5) * VS + ti] = (bf16_t)(R.v32 >> 16);
;     ...
;   load_raw(0, a0); load_raw(1, a1);
;   stage2(a0, bufp(0, 0), 0); stage2(a1, bufp(0, 1), 1);
;   load_raw(2, a0); load_raw(3, a1);
	v_mov_b32_e32 v29, v6
	v_mov_b32_e32 v6, v5
	v_lshlrev_b32_e32 v8, 16, v24
	v_and_b32_e32 v9, 0xffff0000, v24
	v_mov_b32_e32 v28, v4
	v_pk_mul_f32 v[4:5], v[6:7], v[10:11]
	v_mov_b32_e32 v125, v124
	v_pk_fma_f32 v[4:5], v[28:29], v[8:9], v[4:5] neg_lo:[0,0,1] neg_hi:[0,0,1]
	v_lshlrev_b32_e32 v26, 16, v22
	v_pk_mul_f32 v[4:5], v[124:125], v[4:5]
	v_and_b32_e32 v27, 0xffff0000, v22
	v_cvt_pk_bf16_f32 v17, v4, v5
	v_pk_mul_f32 v[4:5], v[6:7], v[8:9]
	v_lshlrev_b32_e32 v22, 16, v21
	v_pk_fma_f32 v[4:5], v[28:29], v[10:11], v[4:5]
	v_and_b32_e32 v23, 0xffff0000, v21
	v_pk_mul_f32 v[4:5], v[124:125], v[4:5]
	s_mov_b32 s6, 0x3db504f3
	v_cvt_pk_bf16_f32 v4, v4, v5
	v_add_u32_e32 v139, 0x5000, v121
	v_pk_mul_f32 v[8:9], v[22:23], s[6:7] op_sel_hi:[1,0]
	ds_write2_b32 v139, v17, v4 offset0:128 offset1:160
	v_pk_mul_f32 v[4:5], v[26:27], s[6:7] op_sel_hi:[1,0]
	v_pk_mul_f32 v[10:11], v[6:7], v[8:9]
	v_mov_b32_e32 v127, v126
	v_pk_fma_f32 v[10:11], v[28:29], v[4:5], v[10:11] neg_lo:[0,0,1] neg_hi:[0,0,1]
	v_pk_mul_f32 v[4:5], v[4:5], v[6:7]
	v_pk_mul_f32 v[22:23], v[126:127], v[10:11]
	v_pk_fma_f32 v[4:5], v[8:9], v[28:29], v[4:5]
	v_cvt_pk_bf16_f32 v17, v22, v23
	v_pk_mul_f32 v[6:7], v[126:127], v[4:5]
	v_add_u32_e32 v140, 0x6000, v121
	v_cvt_pk_bf16_f32 v6, v6, v7
	ds_write2_b32 v140, v17, v6 offset0:192 offset1:224
	v_mul_f32_e32 v6, v117, v10
	v_mul_f32_e32 v4, v117, v4
	v_cvt_pk_bf16_f32 v6, v6, s0
	v_cvt_pk_bf16_f32 v4, v4, s0
	ds_write_b16 v136, v6 offset:29696
	v_mul_f32_e32 v6, v117, v11
	ds_write_b16 v136, v4 offset:31744
	v_mul_f32_e32 v4, v117, v5
	v_cvt_pk_bf16_f32 v6, v6, s0
	v_cvt_pk_bf16_f32 v4, v4, s0
	ds_write_b16 v136, v6 offset:29728
	ds_write_b16 v136, v4 offset:31776
	s_and_saveexec_b64 s[6:7], vcc
	s_xor_b64 s[6:7], exec, s[6:7]
	s_mov_b32 s39, 0x2aaaaaab
	s_movk_i32 s40, 0xff40
	s_movk_i32 s41, 0xff
	s_or_saveexec_b64 s[6:7], s[6:7]
	s_lshl_b32 s8, s8, 7
	s_xor_b64 exec, exec, s[6:7]
	v_mov_b32_e32 v129, v128
	v_add_u32_e32 v4, 0xa000, v25
	ds_write2_b64 v4, v[128:129], v[128:129] offset0:64 offset1:96
	s_or_b64 exec, exec, s[6:7]
	v_readlane_b32 s12, v248, 8
	v_readlane_b32 s14, v248, 10
	v_readlane_b32 s15, v248, 11
	s_add_u32 s6, s14, s2
	s_addc_u32 s7, s15, s3
	s_and_b64 s[2:3], s[0:1], exec
	s_cselect_b32 s2, 0, 0x3000000
	s_add_u32 s2, s6, s2
	v_ashrrev_i32_e32 v4, 6, v111
	v_lshrrev_b32_e32 v5, 31, v111
	s_addc_u32 s3, s7, 0
	v_add_u32_e32 v5, v4, v5
	s_add_u32 s2, s2, s46
	s_waitcnt vmcnt(0)
	ds_write_b16 v137, v0 offset:33792
	ds_write_b16_d16_hi v137, v0 offset:33832
	ds_write_b16 v137, v1 offset:33872
	ds_write_b16_d16_hi v137, v1 offset:33912
	ds_write_b16 v137, v2 offset:33952
	ds_write_b16_d16_hi v137, v2 offset:33992
	v_or_b32_e32 v23, 32, v116
	v_xor_b32_e32 v0, 0x7df, v116
	v_lshrrev_b32_e32 v21, 1, v5
	v_and_b32_e32 v5, -2, v5
	s_addc_u32 s3, s3, 0
	v_cndmask_b32_e64 v2, v0, v23, s[0:1]
	v_sub_u32_e32 v22, v4, v5
	s_add_u32 s42, s2, 0x4000000
	v_or_b32_e32 v4, s18, v2
	v_mov_b64_e32 v[0:1], s[44:45]
	s_addc_u32 s43, s3, 0
	v_mad_u64_u32 v[4:5], s[2:3], v4, s55, v[0:1]
	v_mad_i32_i24 v5, s19, v155, v5
	s_lshl_b32 s94, s8, 1
	v_lshl_add_u64 v[6:7], v[4:5], 0, s[94:95]
	s_mov_b32 s48, s46
	s_mov_b32 s49, s95
	v_lshl_add_u64 v[6:7], v[6:7], 0, v[118:119]
	v_lshlrev_b32_e32 v2, 9, v2
	global_load_dword v242, v[6:7], off
	global_load_dword v241, v[6:7], off offset:128
	global_load_dword v240, v[6:7], off offset:1024
	global_load_dword v239, v[6:7], off offset:1152
	v_lshl_add_u64 v[6:7], s[4:5], 0, v[2:3]
	v_lshl_add_u64 v[4:5], v[4:5], 0, s[48:49]
	v_lshl_add_u64 v[6:7], v[6:7], 0, v[14:15]
	v_lshl_add_u64 v[4:5], v[4:5], 0, v[122:123]
	global_load_dwordx4 v[8:11], v[6:7], off
	global_load_dwordx3 v[112:114], v[4:5], off offset:2048
	v_or_b32_e32 v2, 48, v116
	v_xor_b32_e32 v4, 0x7cf, v116
	v_cndmask_b32_e64 v2, v4, v2, s[0:1]
	v_or_b32_e32 v4, s18, v2
	v_mad_u64_u32 v[0:1], s[2:3], v4, s55, v[0:1]
	v_mad_i32_i24 v1, s19, v155, v1
	v_lshl_add_u64 v[4:5], v[0:1], 0, s[94:95]
	v_lshl_add_u64 v[4:5], v[4:5], 0, v[118:119]
	v_lshlrev_b32_e32 v2, 9, v2
	global_load_dword v238, v[4:5], off
	global_load_dword v237, v[4:5], off offset:128
	global_load_dword v236, v[4:5], off offset:1024
	global_load_dword v235, v[4:5], off offset:1152
	v_lshl_add_u64 v[4:5], s[4:5], 0, v[2:3]
	v_lshl_add_u64 v[4:5], v[4:5], 0, v[14:15]
	v_lshl_add_u64 v[0:1], v[0:1], 0, s[48:49]
	v_lshl_add_u64 v[0:1], v[0:1], 0, v[122:123]
	global_load_dwordx4 v[4:7], v[4:5], off
	s_nop 0
	global_load_dwordx3 v[108:110], v[0:1], off offset:2048
	v_lshlrev_b32_e32 v1, 1, v19
	v_readlane_b32 s2, v247, 30
	v_bfe_u32 v17, v111, 4, 2
	v_lshlrev_b32_e32 v0, 2, v12
	v_add_u32_e32 v2, s2, v1
	v_readlane_b32 s2, v247, 32
	v_readlane_b32 s20, v247, 33
	v_add_u32_e32 v141, 0, v0
	v_add_u32_e32 v144, s2, v0
	v_add_u32_e32 v145, s20, v0
	v_lshlrev_b32_e32 v0, 2, v17
	v_readlane_b32 s13, v248, 9
	v_lshl_add_u64 v[130:131], s[4:5], 0, v[14:15]
	v_or_b32_e32 v15, 2, v0
	v_cmp_gt_u32_e64 s[12:13], v15, v116
	v_or_b32_e32 v15, 3, v0
	v_readlane_b32 s21, v247, 34
	v_cmp_gt_u32_e64 s[8:9], v0, v116
	v_cmp_lt_u32_e64 s[10:11], v0, v116
	v_cmp_gt_u32_e64 s[14:15], v15, v116
	v_mul_lo_u32 v15, v21, 48
	v_lshl_or_b32 v0, v22, 4, v0
	s_movk_i32 s2, 0xc4
	v_lshl_add_u32 v142, v12, 1, v2
	v_readlane_b32 s3, v247, 31
	v_lshl_add_u32 v159, v16, 1, s21
	v_lshlrev_b32_e32 v12, 3, v17
	v_lshlrev_b32_e32 v14, 4, v17
	v_or_b32_e32 v16, v15, v116
	v_add_u32_e32 v13, v15, v13
	v_add_u32_e32 v15, v15, v23
	v_mul_lo_u32 v0, v0, s2
	v_lshlrev_b32_e32 v31, 5, v116
	v_lshl_add_u32 v143, v20, 1, s3
	v_add_lshl_u32 v19, v0, v16, 1
	v_readlane_b32 s2, v247, 35
	v_add_u32_e32 v20, 0xc4, v0
	v_add_u32_e32 v23, 0x188, v0
	v_add_u32_e32 v25, 0x24c, v0
	v_add_lshl_u32 v27, v0, v13, 1
	v_add_lshl_u32 v0, v0, v15, 1
	v_lshl_or_b32 v31, v22, 11, v31
	v_readlane_b32 s25, v247, 36
	v_readlane_b32 s28, v247, 37
	v_add_u32_e32 v203, v2, v14
	v_add_u32_e32 v2, s21, v12
	v_readlane_b32 s21, v247, 38
	s_waitcnt lgkmcnt(0)
	s_barrier
; __device__ __forceinline__ unsigned pk2(float lo, float hi) { f32x2_t v = {lo, hi}; bf16x2_t b = __builtin_convertvector(v, bf16x2_t); return __builtin_bit_cast(unsigned, b); }
; __device__ __forceinline__ float lo_bf(unsigned u) { return __uint_as_float(u << 16); }
; __device__ __forceinline__ float hi_bf(unsigned u) { return __uint_as_float(u & 0xffff0000u); }
; template <int MODE>
; __device__ void scan_unit(int swave, const Params& p, int j, int b, int h, int dir, char* shm) {
;     ...
;   auto ostore = [&](int c, const bf16_t* obuf) {
;     for (int idx = tid; idx < 16 * DV / 4; idx += 512) {
;       const int i = idx / (DV / 4), cc = (idx % (DV / 4)) * 4;
;       uint2 o = *(const uint2*)(obuf + i * OS + cc);
;       if (KS == 2) {
;         const uint2 o2 = *(const uint2*)(obuf + (16 + i) * OS + cc);
;         o.x = pk2(lo_bf(o.x) + lo_bf(o2.x), hi_bf(o.x) + hi_bf(o2.x)); o.y = pk2(lo_bf(o.y) + lo_bf(o2.y), hi_bf(o.y) + hi_bf(o2.y));
;       }
;       *(uint2*)(O + (rowbase + tokof(c, i)) * OLD + cc) = o;
;     }
	v_lshlrev_b32_e32 v17, 7, v22
	v_add_lshl_u32 v21, v20, v16, 1
	v_add_lshl_u32 v28, v20, v13, 1
	v_add_u32_e32 v169, s2, v0
	v_add_lshl_u32 v20, v20, v15, 1
	v_add_u32_e32 v186, s25, v0
	v_add_u32_e32 v199, s28, v0
	v_add_u32_e32 v215, s21, v0
	v_add3_u32 v0, s3, v12, v31
	v_cmp_eq_u32_e64 s[6:7], 0, v22
	v_add_u32_e32 v160, v18, v14
	v_add_u32_e32 v18, 0, v17
	v_add_lshl_u32 v24, v23, v16, 1
	v_add_lshl_u32 v26, v25, v16, 1
	v_add_lshl_u32 v29, v23, v13, 1
	v_add_lshl_u32 v30, v25, v13, 1
	v_add_u32_e32 v170, s2, v20
	v_add_lshl_u32 v23, v23, v15, 1
	v_add_lshl_u32 v25, v25, v15, 1
	v_add_u32_e32 v32, 0, v12
	v_lshlrev_b32_e32 v22, 8, v22
	v_mul_lo_u32 v16, v16, 40
	v_mul_lo_u32 v13, v13, 40
	v_mul_lo_u32 v15, v15, 40
	v_add_u32_e32 v187, s25, v20
	v_add_u32_e32 v200, s28, v20
	v_add_u32_e32 v216, s21, v20
	v_add_u32_e32 v221, 0x200, v0
	v_add_u32_e32 v222, 0x400, v0
	v_add_u32_e32 v223, 0x600, v0
	v_lshlrev_b32_e32 v0, 3, v111
	v_mov_b32_e32 v20, 0
	s_mov_b32 s24, 0
	v_mov_b32_e32 v129, v128
	v_cmp_gt_i32_e64 s[4:5], s52, v111
	v_add_u32_e32 v161, s2, v19
	v_add_u32_e32 v162, s2, v21
	v_add_u32_e32 v163, s2, v24
	v_add_u32_e32 v164, s2, v26
	v_add_u32_e32 v165, s2, v27
	v_add_u32_e32 v166, s2, v28
	v_add_u32_e32 v167, s2, v29
	v_add_u32_e32 v168, s2, v30
	v_add_u32_e32 v171, s2, v23
	v_add_u32_e32 v172, s2, v25
	v_add_u32_e32 v173, v32, v31
	v_add3_u32 v174, 0, v22, v14
	v_add_u32_e32 v175, v32, v16
	v_add_u32_e32 v176, v32, v13
	v_add_u32_e32 v177, v32, v15
	v_add_u32_e32 v178, s25, v19
	v_add_u32_e32 v179, s25, v21
	v_add_u32_e32 v180, s25, v24
	v_add_u32_e32 v181, s25, v26
	v_add_u32_e32 v182, s25, v27
	v_add_u32_e32 v183, s25, v28
	v_add_u32_e32 v184, s25, v29
	v_add_u32_e32 v185, s25, v30
	v_add_u32_e32 v188, s25, v23
	v_add_u32_e32 v189, s25, v25
	v_add3_u32 v190, v18, v17, v14
	v_add_u32_e32 v191, s28, v19
	v_add_u32_e32 v192, s28, v21
	v_add_u32_e32 v193, s28, v24
	v_add_u32_e32 v194, s28, v26
	v_add_u32_e32 v195, s28, v27
	v_add_u32_e32 v196, s28, v28
	v_add_u32_e32 v197, s28, v29
	v_add_u32_e32 v198, s28, v30
	v_add_u32_e32 v201, s28, v23
	v_add_u32_e32 v202, s28, v25
	v_add_u32_e32 v204, v2, v16
	v_add_u32_e32 v205, v2, v13
	v_add_u32_e32 v206, v2, v15
	v_add_u32_e32 v207, s21, v19
	v_add_u32_e32 v208, s21, v21
	v_add_u32_e32 v209, s21, v24
	v_add_u32_e32 v210, s21, v26
	v_add_u32_e32 v211, s21, v27
	v_add_u32_e32 v212, s21, v28
	v_add_u32_e32 v213, s21, v29
	v_add_u32_e32 v214, s21, v30
	v_add_u32_e32 v217, s21, v23
	v_add_u32_e32 v218, s21, v25
	v_add3_u32 v219, s3, v31, v12
	v_add3_u32 v220, s20, v22, v14
	v_add3_u32 v224, v18, v1, v12
	v_add_u32_e32 v138, s28, v0
	v_add_u32_e32 v115, s21, v0
	v_add_u32_e32 v225, s2, v0
	v_add_u32_e32 v226, s25, v0
	v_mov_b32_e32 v21, v20
	v_mov_b32_e32 v22, v20
	v_mov_b32_e32 v23, v20
	v_mov_b32_e32 v32, v20
	v_mov_b32_e32 v33, v20
	v_mov_b32_e32 v34, v20
	v_mov_b32_e32 v35, v20
	v_mov_b32_e32 v36, v20
	v_mov_b32_e32 v37, v20
	v_mov_b32_e32 v38, v20
	v_mov_b32_e32 v39, v20
	v_mov_b32_e32 v44, v20
	v_mov_b32_e32 v45, v20
	v_mov_b32_e32 v46, v20
	v_mov_b32_e32 v47, v20
	v_mov_b32_e32 v48, v20
	v_mov_b32_e32 v49, v20
	v_mov_b32_e32 v50, v20
	v_mov_b32_e32 v51, v20
	v_mov_b32_e32 v52, v20
	v_mov_b32_e32 v53, v20
	v_mov_b32_e32 v54, v20
	v_mov_b32_e32 v55, v20
	v_mov_b32_e32 v56, v20
	v_mov_b32_e32 v57, v20
	v_mov_b32_e32 v58, v20
	v_mov_b32_e32 v59, v20
	v_mov_b32_e32 v60, v20
	v_mov_b32_e32 v61, v20
	v_mov_b32_e32 v62, v20
	v_mov_b32_e32 v63, v20
	v_mov_b32_e32 v64, v20
	v_mov_b32_e32 v65, v20
	v_mov_b32_e32 v66, v20
	v_mov_b32_e32 v67, v20
	v_mov_b32_e32 v40, v20
	v_mov_b32_e32 v41, v20
	v_mov_b32_e32 v42, v20
	v_mov_b32_e32 v43, v20
	v_mov_b32_e32 v28, v20
	v_mov_b32_e32 v29, v20
	v_mov_b32_e32 v30, v20
	v_mov_b32_e32 v31, v20
	v_mov_b32_e32 v24, v20
	v_mov_b32_e32 v25, v20
	v_mov_b32_e32 v26, v20
	v_mov_b32_e32 v27, v20
	s_waitcnt vmcnt(1)
	v_mov_b32_e32 v70, v4
	v_mov_b32_e32 v71, v6
	v_mov_b32_e32 v6, v5
	v_add_u32_e32 v227, 32, v143
	v_add_u32_e32 v228, 0x800, v143
	v_add_u32_e32 v229, 0x820, v143
	v_add_u32_e32 v230, 40, v159
	v_add_u32_e32 v231, 0x50, v159
	v_add_u32_e32 v232, 0x78, v159
	v_add_u32_e32 v233, 0xa0, v159
	v_add_u32_e32 v234, 0xc8, v159
	v_mov_b32_e32 v68, v113
	v_mov_b32_e32 v69, v114
	s_waitcnt vmcnt(0)
	v_mov_b32_e32 v0, v109
	v_mov_b32_e32 v1, v110
	v_lshlrev_b32_e32 v120, 2, v111
	v_mul_hi_i32 v251, v111, s39
	v_lshrrev_b32_e32 v249, 31, v251
	v_ashrrev_i32_e32 v251, 3, v251
	v_add_u32_e32 v251, v251, v249
	v_lshlrev_b32_e32 v243, 3, v251
	v_mul_lo_u32 v249, v251, s40
	v_add_u32_e32 v249, v249, v120
	v_sub_u32_e32 v250, 15, v251
	v_cndmask_b32_e64 v250, v250, v251, s[0:1]
	v_mul_u32_u24_e32 v250, 0x600, v250
	v_lshl_add_u32 v249, v249, 1, v250
	v_add_u32_e32 v251, 0x200, v111
	v_mul_hi_i32 v251, v251, s39
	v_lshrrev_b32_e32 v250, 31, v251
	v_ashrrev_i32_e32 v251, 3, v251
	v_add_u32_e32 v251, v251, v250
	v_sub_u32_e32 v250, 15, v251
	v_cndmask_b32_e64 v250, v250, v251, s[0:1]
	v_mul_u32_u24_e32 v250, 0x600, v250
	v_mul_lo_u32 v244, v251, s40
	v_add_u32_e32 v244, v244, v120
	v_add_u32_e32 v244, 0x800, v244
	v_lshl_add_u32 v250, v244, 1, v250
	v_lshlrev_b32_e32 v244, 3, v251
	v_add_u32_e32 v244, 0x1000, v244
	s_branch .LBB0_571

; __device__ __forceinline__ unsigned pk2(float lo, float hi) { f32x2_t v = {lo, hi}; bf16x2_t b = __builtin_convertvector(v, bf16x2_t); return __builtin_bit_cast(unsigned, b); }
; __device__ __forceinline__ float lo_bf(unsigned u) { return __uint_as_float(u << 16); }
; __device__ __forceinline__ float hi_bf(unsigned u) { return __uint_as_float(u & 0xffff0000u); }
; template <int MODE>
; __device__ void scan_unit(int swave, const Params& p, int j, int b, int h, int dir, char* shm) {
;     ...
;   auto ostore = [&](int c, const bf16_t* obuf) {
;     for (int idx = tid; idx < 16 * DV / 4; idx += 512) {
;       const int i = idx / (DV / 4), cc = (idx % (DV / 4)) * 4;
;       uint2 o = *(const uint2*)(obuf + i * OS + cc);
;       if (KS == 2) {
;         const uint2 o2 = *(const uint2*)(obuf + (16 + i) * OS + cc);
;         o.x = pk2(lo_bf(o.x) + lo_bf(o2.x), hi_bf(o.x) + hi_bf(o2.x)); o.y = pk2(lo_bf(o.y) + lo_bf(o2.y), hi_bf(o.y) + hi_bf(o2.y));
;       }
;       *(uint2*)(O + (rowbase + tokof(c, i)) * OLD + cc) = o;
;     }
;     ...
;   auto body = [&](int it, Raw& c0, Raw& c1, Raw& n0, Raw& n1) {
;     touch(c0); touch(c1);
;     __builtin_amdgcn_sched_barrier(0);
;     const int cA = 2 * it + 4 < NCH ? 2 * it + 4 : NCH - 2;
;     load_raw(cA, n0); load_raw(cA + 1, n1);
;     if (it > 0) { ostore(2 * it - 2, obp((it - 1) & 1, 0)); ostore(2 * it - 1, obp((it - 1) & 1, 1)); }
.LBB0_571:
	s_cmp_gt_u32 s24, 61
	s_cselect_b64 s[50:51], -1, 0
	s_lshl_b32 s25, s24, 5
	s_add_i32 s20, s25, 64
	s_cmp_lt_u32 s24, 62
	s_cselect_b64 s[68:69], -1, 0
	s_and_b64 s[2:3], s[68:69], exec
	s_cselect_b32 s2, s20, 0x7e0
	v_or_b32_e32 v2, s2, v116
	v_sub_u32_e32 v4, 0x7ff, v2
	v_cndmask_b32_e64 v4, v4, v2, s[0:1]
	v_ashrrev_i32_e32 v5, 31, v4
	v_lshl_add_u64 v[12:13], s[18:19], 0, v[4:5]
	v_mov_b64_e32 v[14:15], s[44:45]
	v_mad_u64_u32 v[16:17], s[2:3], v12, s55, v[14:15]
	v_mad_i32_i24 v17, v13, s55, v17
	v_lshl_add_u64 v[12:13], v[16:17], 0, s[94:95]
	v_lshlrev_b32_e32 v4, 6, v4
	v_lshl_add_u64 v[12:13], v[12:13], 0, v[118:119]
	v_ashrrev_i32_e32 v5, 31, v4
	global_load_dword v107, v[12:13], off
	global_load_dword v106, v[12:13], off offset:128
	global_load_dword v105, v[12:13], off offset:1024
	global_load_dword v104, v[12:13], off offset:1152
	v_lshl_add_u64 v[4:5], v[4:5], 3, v[130:131]
	v_lshl_add_u64 v[12:13], v[16:17], 0, s[48:49]
	v_or_b32_e32 v2, 16, v2
	v_lshl_add_u64 v[12:13], v[12:13], 0, v[122:123]
	global_load_dwordx4 v[16:19], v[4:5], off
	global_load_dwordx3 v[98:100], v[12:13], off offset:2048
	v_sub_u32_e32 v4, 0x7ff, v2
	v_cndmask_b32_e64 v4, v4, v2, s[0:1]
	v_ashrrev_i32_e32 v5, 31, v4
	v_lshl_add_u64 v[12:13], s[18:19], 0, v[4:5]
	v_mad_u64_u32 v[14:15], s[2:3], v12, s55, v[14:15]
	v_mad_i32_i24 v15, v13, s55, v15
	v_lshl_add_u64 v[12:13], v[14:15], 0, s[94:95]
	v_lshl_add_u64 v[12:13], v[12:13], 0, v[118:119]
	v_lshlrev_b32_e32 v4, 6, v4
	global_load_dword v103, v[12:13], off
	global_load_dword v102, v[12:13], off offset:128
	global_load_dword v101, v[12:13], off offset:1024
	global_load_dword v97, v[12:13], off offset:1152
	v_ashrrev_i32_e32 v5, 31, v4
	v_lshl_add_u64 v[4:5], v[4:5], 3, v[130:131]
	v_lshl_add_u64 v[12:13], v[14:15], 0, s[48:49]
	v_lshl_add_u64 v[72:73], v[12:13], 0, v[122:123]
	global_load_dwordx4 v[12:15], v[4:5], off
	global_load_dwordx3 v[94:96], v[72:73], off offset:2048
	s_cmp_lg_u32 s24, 0
	s_cselect_b64 s[2:3], -1, 0
	s_and_b64 s[20:21], s[4:5], s[2:3]
	s_and_saveexec_b64 s[2:3], s[20:21]
	s_movk_i32 s33, 0x600
	s_cbranch_execz .LBB0_576
	s_sub_i32 s20, s25, 32
	s_sub_i32 s34, 0x7f0, s20
	s_cmp_lg_u64 s[0:1], 0
	s_cselect_b32 s34, s20, s34
	s_add_i32 s34, s34, s18
	s_mul_i32 s35, s34, 0x600
	s_add_u32 s28, s42, s35
	s_addc_u32 s29, s43, 0
	v_add_u32_e32 v2, v138, v243
	v_add_u32_e32 v82, v138, v244
	ds_read_b64 v[74:75], v2
	ds_read_b64 v[76:77], v2 offset:6272
	ds_read_b64 v[4:5], v82
	ds_read_b64 v[72:73], v82 offset:6272
	s_waitcnt lgkmcnt(2)
	v_lshlrev_b32_e32 v78, 16, v74
	v_lshlrev_b32_e32 v80, 16, v76
	v_and_b32_e32 v79, 0xffff0000, v74
	v_and_b32_e32 v81, 0xffff0000, v76
	v_pk_add_f32 v[78:79], v[78:79], v[80:81]
	v_lshlrev_b32_e32 v80, 16, v77
	v_and_b32_e32 v81, 0xffff0000, v77
	v_cvt_pk_bf16_f32 v74, v78, v79
	v_lshlrev_b32_e32 v78, 16, v75
	v_and_b32_e32 v79, 0xffff0000, v75
	v_pk_add_f32 v[78:79], v[78:79], v[80:81]
	s_nop 0
	v_cvt_pk_bf16_f32 v75, v78, v79
	s_nop 0
	global_store_dwordx2 v249, v[74:75], s[28:29]
	v_cmp_gt_u32_e32 vcc, 0x100, v111
	s_and_saveexec_b64 s[34:35], vcc
	s_cbranch_execz .Lros_skip_a
	s_waitcnt lgkmcnt(0)
	v_lshlrev_b32_e32 v78, 16, v4
	v_lshlrev_b32_e32 v80, 16, v72
	v_and_b32_e32 v79, 0xffff0000, v4
	v_and_b32_e32 v81, 0xffff0000, v72
	v_pk_add_f32 v[78:79], v[78:79], v[80:81]
	v_lshlrev_b32_e32 v80, 16, v73
	v_and_b32_e32 v81, 0xffff0000, v73
	v_cvt_pk_bf16_f32 v4, v78, v79
	v_lshlrev_b32_e32 v78, 16, v5
	v_and_b32_e32 v79, 0xffff0000, v5
	v_pk_add_f32 v[78:79], v[78:79], v[80:81]
	s_nop 0
	v_cvt_pk_bf16_f32 v5, v78, v79
	s_nop 0
	global_store_dwordx2 v250, v[4:5], s[28:29]
.Lros_skip_a:
	s_or_b64 exec, exec, s[34:35]
	s_waitcnt lgkmcnt(0)
	s_add_i32 s20, s25, -16
	s_sub_i32 s34, 0x7f0, s20
	s_cmp_lg_u64 s[0:1], 0
	s_cselect_b32 s34, s20, s34
	s_add_i32 s34, s34, s18
	s_mul_i32 s35, s34, 0x600
	s_add_u32 s28, s42, s35
	s_addc_u32 s29, s43, 0
	v_add_u32_e32 v2, v115, v243
	v_add_u32_e32 v82, v115, v244
	ds_read_b64 v[74:75], v2
	ds_read_b64 v[76:77], v2 offset:6272
	ds_read_b64 v[4:5], v82
	ds_read_b64 v[72:73], v82 offset:6272
	s_waitcnt lgkmcnt(2)
	v_lshlrev_b32_e32 v78, 16, v74
	v_lshlrev_b32_e32 v80, 16, v76
	v_and_b32_e32 v79, 0xffff0000, v74
	v_and_b32_e32 v81, 0xffff0000, v76
	v_pk_add_f32 v[78:79], v[78:79], v[80:81]
	v_lshlrev_b32_e32 v80, 16, v77
	v_and_b32_e32 v81, 0xffff0000, v77
	v_cvt_pk_bf16_f32 v74, v78, v79
	v_lshlrev_b32_e32 v78, 16, v75
	v_and_b32_e32 v79, 0xffff0000, v75
	v_pk_add_f32 v[78:79], v[78:79], v[80:81]
	s_nop 0
	v_cvt_pk_bf16_f32 v75, v78, v79
	s_nop 0
	global_store_dwordx2 v249, v[74:75], s[28:29]
	v_cmp_gt_u32_e32 vcc, 0x100, v111
	s_and_saveexec_b64 s[34:35], vcc
	s_cbranch_execz .Lros_skip_b
	s_waitcnt lgkmcnt(0)
	v_lshlrev_b32_e32 v78, 16, v4
	v_lshlrev_b32_e32 v80, 16, v72
	v_and_b32_e32 v79, 0xffff0000, v4
	v_and_b32_e32 v81, 0xffff0000, v72
	v_pk_add_f32 v[78:79], v[78:79], v[80:81]
	v_lshlrev_b32_e32 v80, 16, v73
	v_and_b32_e32 v81, 0xffff0000, v73
	v_cvt_pk_bf16_f32 v4, v78, v79
	v_lshlrev_b32_e32 v78, 16, v5
	v_and_b32_e32 v79, 0xffff0000, v5
	v_pk_add_f32 v[78:79], v[78:79], v[80:81]
	s_nop 0
	v_cvt_pk_bf16_f32 v5, v78, v79
	s_nop 0
	global_store_dwordx2 v250, v[4:5], s[28:29]
; __device__ __forceinline__ unsigned pk2(float lo, float hi) { f32x2_t v = {lo, hi}; bf16x2_t b = __builtin_convertvector(v, bf16x2_t); return __builtin_bit_cast(unsigned, b); }
; __device__ __forceinline__ bf16_t f2bf(float f) { return (bf16_t)(pk2(f, 0.f) & 0xffffu); }
; __device__ __forceinline__ float lo_bf(unsigned u) { return __uint_as_float(u << 16); }
; __device__ __forceinline__ float hi_bf(unsigned u) { return __uint_as_float(u & 0xffff0000u); }
; template <int MODE>
; __device__ void scan_unit(int swave, const Params& p, int j, int b, int h, int dir, char* shm) {
;     ...
;       const float KSC = 0.08838834764831845f;
;       const float qx0 = lo_bf(R.q), qx1 = hi_bf(R.q), qy0 = lo_bf(R.q2), qy1 = hi_bf(R.q2);
;       const float kx0 = lo_bf(R.k) * KSC, kx1 = hi_bf(R.k) * KSC, ky0 = lo_bf(R.k2) * KSC, ky1 = hi_bf(R.k2) * KSC;
;       const float c0 = R.cs.x, sn0 = R.cs.y, c1 = R.cs.z, sn1 = R.cs.w;
;       const float qa0 = qx0 * c0 - qy0 * sn0, qb0 = qx0 * sn0 + qy0 * c0, qa1 = qx1 * c1 - qy1 * sn1, qb1 = qx1 * sn1 + qy1 * c1;
;       const float ka0 = kx0 * c0 - ky0 * sn0, kb0 = kx0 * sn0 + ky0 * c0, ka1 = kx1 * c1 - ky1 * sn1, kb1 = kx1 * sn1 + ky1 * c1;
;       const float ein = ret_ein, eti = ret_eti, eout = ret_eout;
;       *(unsigned*)(qin + ti * QS + dp) = pk2(qa0 * ein, qa1 * ein); *(unsigned*)(qin + ti * QS + 64 + dp) = pk2(qb0 * ein, qb1 * ein);
;       *(unsigned*)(ktil + ti * QS + dp) = pk2(ka0 * eti, ka1 * eti); *(unsigned*)(ktil + ti * QS + 64 + dp) = pk2(kb0 * eti, kb1 * eti);
;       koutT[dp * 16 + ti] = f2bf(ka0 * eout); koutT[(dp + 1) * 16 + ti] = f2bf(ka1 * eout);
;       koutT[(64 + dp) * 16 + ti] = f2bf(kb0 * eout); koutT[(65 + dp) * 16 + ti] = f2bf(kb1 * eout);
;       if (ti == 0) { const float dd = ret_dd; *(float2*)(dec + dp) = make_float2(dd, dd); *(float2*)(dec + 64 + dp) = make_float2(dd, dd); }
;       const int c6 = vg * 6;
;       vT[(c6 + 0) * VS + ti] = (bf16_t)(R.v30 & 0xffff); vT[(c6 + 1) * VS + ti] = (bf16_t)(R.v30 >> 16);
;       vT[(c6 + 2) * VS + ti] = (bf16_t)(R.v31 & 0xffff); vT[(c6 + 3) * VS + ti] = (bf16_t)(R.v31 >> 16);
;       vT[(c6 + 4) * VS + ti] = (bf16_t)(R.v32 & 0xffff); vT[(c6 + 5) * VS + ti] = (bf16_t)(R.v32 >> 16);
.Lros_skip_b:
	s_or_b64 exec, exec, s[34:35]
	s_waitcnt lgkmcnt(0)
.LBB0_576:
	s_or_b64 exec, exec, s[2:3]
	v_mov_b32_e32 v4, v9
	v_mov_b32_e32 v5, v11
	v_lshlrev_b32_e32 v72, 16, v241
	v_and_b32_e32 v73, 0xffff0000, v241
	v_mov_b32_e32 v9, v10
	v_lshlrev_b32_e32 v10, 16, v242
	v_and_b32_e32 v11, 0xffff0000, v242
	v_pk_mul_f32 v[78:79], v[4:5], v[72:73]
	v_lshlrev_b32_e32 v74, 16, v240
	v_pk_fma_f32 v[78:79], v[8:9], v[10:11], v[78:79] neg_lo:[0,0,1] neg_hi:[0,0,1]
	v_pk_mul_f32 v[10:11], v[4:5], v[10:11]
	v_pk_mul_f32 v[78:79], v[124:125], v[78:79]
	v_pk_fma_f32 v[10:11], v[8:9], v[72:73], v[10:11]
	v_and_b32_e32 v75, 0xffff0000, v240
	v_pk_mul_f32 v[10:11], v[124:125], v[10:11]
	v_lshlrev_b32_e32 v76, 16, v239
	v_and_b32_e32 v77, 0xffff0000, v239
	v_cvt_pk_bf16_f32 v2, v78, v79
	v_cvt_pk_bf16_f32 v10, v10, v11
	v_add_u32_e32 v11, 0xa400, v121
	s_mov_b32 s2, 0x3db504f3
	ds_write2_b32 v11, v2, v10 offset1:32
	v_pk_mul_f32 v[10:11], v[74:75], s[2:3] op_sel_hi:[1,0]
	v_pk_mul_f32 v[72:73], v[76:77], s[2:3] op_sel_hi:[1,0]
	s_nop 0
	v_pk_mul_f32 v[74:75], v[4:5], v[72:73]
	v_pk_mul_f32 v[4:5], v[4:5], v[10:11]
	v_pk_fma_f32 v[74:75], v[8:9], v[10:11], v[74:75] neg_lo:[0,0,1] neg_hi:[0,0,1]
	v_pk_fma_f32 v[4:5], v[8:9], v[72:73], v[4:5]
	v_pk_mul_f32 v[76:77], v[126:127], v[74:75]
	v_pk_mul_f32 v[8:9], v[126:127], v[4:5]
	v_cvt_pk_bf16_f32 v2, v76, v77
	v_cvt_pk_bf16_f32 v8, v8, v9
	v_add_u32_e32 v9, 0xb400, v121
	ds_write2_b32 v9, v2, v8 offset0:64 offset1:96
	v_mul_f32_e32 v2, v117, v74
	v_cvt_pk_bf16_f32 v2, v2, s0
	ds_write_b16 v136, v2 offset:50688
	v_mul_f32_e32 v2, v117, v75
	v_cvt_pk_bf16_f32 v2, v2, s0
	ds_write_b16 v136, v2 offset:50720
	v_mul_f32_e32 v2, v117, v4
	v_cvt_pk_bf16_f32 v2, v2, s0
	ds_write_b16 v136, v2 offset:52736
	v_mul_f32_e32 v2, v117, v5
	v_cvt_pk_bf16_f32 v2, v2, s0
	ds_write_b16 v136, v2 offset:52768
	s_and_saveexec_b64 s[2:3], s[16:17]
	v_add_u32_e32 v2, 0xf000, v141
	ds_write2_b64 v2, v[128:129], v[128:129] offset0:128 offset1:160
	s_or_b64 exec, exec, s[2:3]
	v_lshlrev_b32_e32 v8, 16, v237
	v_and_b32_e32 v9, 0xffff0000, v237
	v_lshlrev_b32_e32 v4, 16, v238
	v_and_b32_e32 v5, 0xffff0000, v238
	v_pk_mul_f32 v[72:73], v[6:7], v[8:9]
	ds_write_b16 v137, v112 offset:54784
	ds_write_b16_d16_hi v137, v112 offset:54824
	ds_write_b16 v137, v68 offset:54864
	ds_write_b16_d16_hi v137, v68 offset:54904
	ds_write_b16 v137, v69 offset:54944
	ds_write_b16_d16_hi v137, v69 offset:54984
	v_pk_fma_f32 v[72:73], v[70:71], v[4:5], v[72:73] neg_lo:[0,0,1] neg_hi:[0,0,1]
	v_pk_mul_f32 v[4:5], v[6:7], v[4:5]
	v_lshlrev_b32_e32 v68, 16, v235
	v_pk_fma_f32 v[4:5], v[70:71], v[8:9], v[4:5]
	v_and_b32_e32 v69, 0xffff0000, v235
	v_pk_mul_f32 v[72:73], v[124:125], v[72:73]
	v_pk_mul_f32 v[4:5], v[124:125], v[4:5]
	s_mov_b32 s2, 0x3db504f3
	v_lshlrev_b32_e32 v10, 16, v236
	v_and_b32_e32 v11, 0xffff0000, v236
	v_cvt_pk_bf16_f32 v2, v72, v73
	v_cvt_pk_bf16_f32 v4, v4, v5
	v_add_u32_e32 v5, 0xf400, v121
	v_pk_mul_f32 v[8:9], v[68:69], s[2:3] op_sel_hi:[1,0]
	ds_write2_b32 v5, v2, v4 offset0:128 offset1:160
	v_pk_mul_f32 v[4:5], v[10:11], s[2:3] op_sel_hi:[1,0]
	v_pk_mul_f32 v[10:11], v[6:7], v[8:9]
	s_nop 0
	v_pk_fma_f32 v[10:11], v[70:71], v[4:5], v[10:11] neg_lo:[0,0,1] neg_hi:[0,0,1]
	v_pk_mul_f32 v[4:5], v[6:7], v[4:5]
	v_pk_mul_f32 v[68:69], v[126:127], v[10:11]
	v_pk_fma_f32 v[4:5], v[70:71], v[8:9], v[4:5]
	v_cvt_pk_bf16_f32 v2, v68, v69
	v_pk_mul_f32 v[6:7], v[126:127], v[4:5]
	s_nop 0
	v_cvt_pk_bf16_f32 v6, v6, v7
	ds_write2_b32 v142, v2, v6 offset1:32
	v_mul_f32_e32 v2, v117, v10
	v_cvt_pk_bf16_f32 v2, v2, s0
	ds_write_b16 v143, v2
	v_mul_f32_e32 v2, v117, v11
	v_cvt_pk_bf16_f32 v2, v2, s0
	ds_write_b16 v227, v2
	v_mul_f32_e32 v2, v117, v4
	v_cvt_pk_bf16_f32 v2, v2, s0
	ds_write_b16 v228, v2
	v_mul_f32_e32 v2, v117, v5
	v_cvt_pk_bf16_f32 v2, v2, s0
	ds_write_b16 v229, v2
	s_and_saveexec_b64 s[2:3], s[16:17]
	s_cbranch_execz .LBB0_580
	ds_write_b64 v145, v[128:129]
	ds_write_b64 v144, v[128:129]

; __device__ __forceinline__ unsigned pk2(float lo, float hi) { f32x2_t v = {lo, hi}; bf16x2_t b = __builtin_convertvector(v, bf16x2_t); return __builtin_bit_cast(unsigned, b); }
; __device__ __forceinline__ bf16_t f2bf(float f) { return (bf16_t)(pk2(f, 0.f) & 0xffffu); }
; template <int MODE>
; __device__ void scan_unit(int swave, const Params& p, int j, int b, int h, int dir, char* shm) {
;     ...
; #pragma unroll
;     for (int m = 0; m < 2; ++m)
; #pragma unroll
;       for (int t = 0; t < NVT; ++t) {
;         const f32x4 s0 = S[2 * m][t], s1 = S[2 * m + 1][t];
;         union { unsigned u[4]; bf16x8 v; } cv;
;         cv.u[0] = pk2(s0[0], s0[1]); cv.u[1] = pk2(s0[2], s0[3]); cv.u[2] = pk2(s1[0], s1[1]); cv.u[3] = pk2(s1[2], s1[3]);
;         o[t] = __builtin_amdgcn_mfma_f32_16x16x32_bf16(Aq[m], cv.v, o[t], 0, 0, 0);
;       }
; #pragma unroll
;     for (int t = 0; t < NVT; ++t)
; #pragma unroll
;       for (int jj = 0; jj < 4; ++jj) obuf[(wk * 16 + q4 * 4 + jj) * OS + (vt0 + t) * 16 + r] = f2bf(o[t][jj]);
; #pragma unroll
;     for (int kt = 0; kt < 4; ++kt) {
;       const uint2 kk = *(const uint2*)(koutT + (slab + kt * 16 + r) * 16 + q4 * 4);
;       const bf16x8 Ak = {(short)(kk.x & 0xffff), (short)(kk.x >> 16), (short)(kk.y & 0xffff), (short)(kk.y >> 16), 0, 0, 0, 0};
;       const f32x4 dc = *(const f32x4*)(dec + slab + kt * 16 + q4 * 4);
; #pragma unroll
;       for (int t = 0; t < NVT; ++t) S[kt][t] = __builtin_amdgcn_mfma_f32_16x16x32_bf16(Ak, Bv[t], S[kt][t] * dc, 0, 0, 0);
;     ...
;   auto body = [&](int it, Raw& c0, Raw& c1, Raw& n0, Raw& n1) {
;     touch(c0); touch(c1);
;     __builtin_amdgcn_sched_barrier(0);
;     const int cA = 2 * it + 4 < NCH ? 2 * it + 4 : NCH - 2;
;     load_raw(cA, n0); load_raw(cA + 1, n1);
;     if (it > 0) { ostore(2 * it - 2, obp((it - 1) & 1, 0)); ostore(2 * it - 1, obp((it - 1) & 1, 1)); }
;     stage2(c0, bufp((it + 1) & 1, 0), 0); stage2(c1, bufp((it + 1) & 1, 1), 0);
;     compute(bufp(it & 1, 0), obp(it & 1, 0)); compute(bufp(it & 1, 1), obp(it & 1, 1));
;     lds_barrier();
.LBB0_596:
	s_or_b64 exec, exec, s[2:3]
	s_waitcnt lgkmcnt(1)
	v_bfi_b32 v26, s30, v26, v26
	s_waitcnt lgkmcnt(0)
	v_bfi_b32 v22, s30, v22, v22
	v_cvt_pk_bf16_f32 v80, v4, v5
	v_cvt_pk_bf16_f32 v81, v6, v7
	v_cvt_pk_bf16_f32 v82, v40, v41
	v_cvt_pk_bf16_f32 v83, v42, v43
	s_nop 1
	v_mfma_f32_16x16x32_bf16 v[36:39], v[24:27], v[80:83], v[36:39]
	v_cvt_pk_bf16_f32 v80, v8, v9
	v_cvt_pk_bf16_f32 v81, v10, v11
	v_cvt_pk_bf16_f32 v82, v60, v61
	v_cvt_pk_bf16_f32 v83, v62, v63
	s_nop 1
	v_mfma_f32_16x16x32_bf16 v[32:35], v[24:27], v[80:83], v[32:35]
	v_cvt_pk_bf16_f32 v80, v28, v29
	v_cvt_pk_bf16_f32 v81, v30, v31
	v_cvt_pk_bf16_f32 v82, v64, v65
	v_cvt_pk_bf16_f32 v83, v66, v67
	s_nop 1
	v_mfma_f32_16x16x32_bf16 v[24:27], v[24:27], v[80:83], v[44:47]
	s_nop 2
	v_cvt_pk_bf16_f32 v44, v52, v53
	v_cvt_pk_bf16_f32 v45, v54, v55
	v_cvt_pk_bf16_f32 v46, v68, v69
	v_cvt_pk_bf16_f32 v47, v70, v71
	s_nop 1
	v_mfma_f32_16x16x32_bf16 v[36:39], v[20:23], v[44:47], v[36:39]
	v_cvt_pk_bf16_f32 v44, v48, v49
	v_cvt_pk_bf16_f32 v45, v50, v51
	v_cvt_pk_bf16_f32 v46, v72, v73
	v_cvt_pk_bf16_f32 v47, v74, v75
	s_nop 1
	v_mfma_f32_16x16x32_bf16 v[32:35], v[20:23], v[44:47], v[32:35]
	v_cvt_pk_bf16_f32 v44, v56, v57
	v_cvt_pk_bf16_f32 v45, v58, v59
	v_cvt_pk_bf16_f32 v46, v76, v77
	v_cvt_pk_bf16_f32 v47, v78, v79
	s_nop 1
	v_mfma_f32_16x16x32_bf16 v[20:23], v[20:23], v[44:47], v[24:27]
	s_nop 2
	v_cvt_pk_bf16_f32 v24, v36, s0
	ds_write_b16 v178, v24
	v_cvt_pk_bf16_f32 v24, v37, s0
	ds_write_b16 v179, v24
	v_cvt_pk_bf16_f32 v24, v38, s0
	ds_write_b16 v180, v24
	v_cvt_pk_bf16_f32 v24, v39, s0
	ds_write_b16 v181, v24
	v_cvt_pk_bf16_f32 v24, v32, s0
	ds_write_b16 v182, v24
	v_cvt_pk_bf16_f32 v24, v33, s0
	ds_write_b16 v183, v24
	v_cvt_pk_bf16_f32 v24, v34, s0
	ds_write_b16 v184, v24
	v_cvt_pk_bf16_f32 v24, v35, s0
	v_cvt_pk_bf16_f32 v20, v20, s0
	ds_write_b16 v185, v24
	ds_write_b16 v186, v20
	v_cvt_pk_bf16_f32 v20, v21, s0
	ds_write_b16 v187, v20
	v_cvt_pk_bf16_f32 v20, v22, s0
	ds_write_b16 v188, v20
	v_cvt_pk_bf16_f32 v20, v23, s0
	ds_write_b16 v189, v20
	ds_read2st64_b64 v[32:35], v173 offset0:58 offset1:59
	ds_read2st64_b64 v[80:83], v173 offset0:60 offset1:61
	ds_read_b128 v[44:47], v190 offset:41472
	ds_read_b128 v[236:239], v190 offset:41536
	v_mov_b32_e32 v38, v3
	s_waitcnt lgkmcnt(3)
	v_mov_b32_e32 v36, v32
	v_mov_b32_e32 v37, v33
	v_mov_b32_e32 v39, v3
	s_waitcnt lgkmcnt(1)
	v_pk_mul_f32 v[6:7], v[6:7], v[46:47]
	v_pk_mul_f32 v[4:5], v[4:5], v[44:45]
	s_nop 1
	v_mfma_f32_16x16x32_bf16 v[20:23], v[36:39], v[0:3], v[4:7]
	s_nop 2
	v_mul_f32_e64 v6, v10, v46
	v_mul_f32_e64 v7, v11, v47
	v_pk_mul_f32 v[4:5], v[8:9], v[44:45]
	s_waitcnt lgkmcnt(0)
	v_pk_mul_f32 v[10:11], v[42:43], v[238:239]
	v_pk_mul_f32 v[8:9], v[40:41], v[236:237]
	v_mfma_f32_16x16x32_bf16 v[24:27], v[36:39], v[88:91], v[4:7]
	s_nop 2
	v_mul_f32_e64 v6, v30, v46
	v_mul_f32_e64 v7, v31, v47
	v_pk_mul_f32 v[4:5], v[28:29], v[44:45]
	s_nop 1
	v_mfma_f32_16x16x32_bf16 v[28:31], v[36:39], v[84:87], v[4:7]
	s_nop 2
	v_mov_b32_e32 v4, v34
	v_mov_b32_e32 v5, v35
	v_mov_b32_e32 v6, v3
	v_mov_b32_e32 v7, v3
	s_nop 1
	v_mfma_f32_16x16x32_bf16 v[32:35], v[4:7], v[0:3], v[8:11]
	s_nop 2
	v_mul_f32_e64 v10, v62, v238
	v_mul_f32_e64 v11, v63, v239
	v_pk_mul_f32 v[8:9], v[60:61], v[236:237]
	v_mov_b32_e32 v60, v80
	v_mov_b32_e32 v61, v81
	v_mfma_f32_16x16x32_bf16 v[36:39], v[4:7], v[88:91], v[8:11]
	v_mov_b32_e32 v62, v3
	v_mov_b32_e32 v63, v3
	s_nop 0
	v_pk_mul_f32 v[10:11], v[66:67], v[238:239]
	v_pk_mul_f32 v[8:9], v[64:65], v[236:237]
	ds_read_b128 v[236:239], v190 offset:41600
	s_nop 0
	v_mfma_f32_16x16x32_bf16 v[64:67], v[4:7], v[84:87], v[8:11]
	ds_read_b128 v[4:7], v190 offset:41664
	s_waitcnt lgkmcnt(0)
	s_barrier
	s_waitcnt vmcnt(6)
	s_waitcnt lgkmcnt(1)
	v_pk_mul_f32 v[10:11], v[54:55], v[238:239]
	v_pk_mul_f32 v[8:9], v[52:53], v[236:237]
	s_waitcnt lgkmcnt(0)
	v_pk_mul_f32 v[54:55], v[70:71], v[6:7]
	v_pk_mul_f32 v[52:53], v[68:69], v[4:5]
	v_mfma_f32_16x16x32_bf16 v[40:43], v[60:63], v[0:3], v[8:11]
	s_waitcnt vmcnt(0)
	s_nop 1
	v_pk_mul_f32 v[10:11], v[50:51], v[238:239]
	v_pk_mul_f32 v[8:9], v[48:49], v[236:237]
	s_nop 1
	v_mfma_f32_16x16x32_bf16 v[44:47], v[60:63], v[88:91], v[8:11]
	s_nop 2
	v_mul_f32_e64 v10, v58, v238
	v_mul_f32_e64 v11, v59, v239
	v_pk_mul_f32 v[8:9], v[56:57], v[236:237]
	v_pk_mul_f32 v[58:59], v[74:75], v[6:7]
	v_pk_mul_f32 v[56:57], v[72:73], v[4:5]
	v_mfma_f32_16x16x32_bf16 v[48:51], v[60:63], v[84:87], v[8:11]
	v_mul_f32_e64 v6, v78, v6
	v_mul_f32_e64 v7, v79, v7
	v_pk_mul_f32 v[4:5], v[76:77], v[4:5]
	v_mov_b32_e32 v8, v82
	v_mov_b32_e32 v9, v83
	v_mov_b32_e32 v10, v3
	v_mov_b32_e32 v11, v3
	s_nop 1
	v_mfma_f32_16x16x32_bf16 v[52:55], v[8:11], v[0:3], v[52:55]
	v_mfma_f32_16x16x32_bf16 v[56:59], v[8:11], v[88:91], v[56:59]
	v_mfma_f32_16x16x32_bf16 v[60:63], v[8:11], v[84:87], v[4:7]
	s_add_i32 s20, s25, 0x60
	s_and_b64 s[2:3], s[68:69], exec
	s_cselect_b32 s2, s20, 0x7e0
	v_or_b32_e32 v2, s2, v116
	v_sub_u32_e32 v0, 0x7ff, v2
	v_cndmask_b32_e64 v0, v0, v2, s[0:1]
	v_ashrrev_i32_e32 v1, 31, v0
	v_lshl_add_u64 v[4:5], s[18:19], 0, v[0:1]
	v_mov_b64_e32 v[6:7], s[44:45]
	v_mad_u64_u32 v[8:9], s[2:3], v4, s55, v[6:7]
	v_mad_i32_i24 v9, v5, s55, v9
	v_lshl_add_u64 v[4:5], v[8:9], 0, s[94:95]
	v_lshlrev_b32_e32 v0, 6, v0
	v_lshl_add_u64 v[4:5], v[4:5], 0, v[118:119]
	v_ashrrev_i32_e32 v1, 31, v0
	s_mov_b32 s47, s95
	global_load_dword v242, v[4:5], off
	global_load_dword v241, v[4:5], off offset:128
	global_load_dword v240, v[4:5], off offset:1024
	global_load_dword v239, v[4:5], off offset:1152
	v_lshl_add_u64 v[0:1], v[0:1], 3, v[130:131]
	v_lshl_add_u64 v[4:5], v[8:9], 0, s[46:47]
	v_lshl_add_u64 v[4:5], v[4:5], 0, v[122:123]
	global_load_dwordx4 v[8:11], v[0:1], off
	global_load_dwordx3 v[112:114], v[4:5], off offset:2048
	v_or_b32_e32 v0, 16, v2
	v_sub_u32_e32 v1, 0x7ff, v0
	v_cndmask_b32_e64 v0, v1, v0, s[0:1]
	v_ashrrev_i32_e32 v1, 31, v0
	v_lshl_add_u64 v[4:5], s[18:19], 0, v[0:1]
	v_mad_u64_u32 v[6:7], s[2:3], v4, s55, v[6:7]
	v_mad_i32_i24 v7, v5, s55, v7
	v_lshl_add_u64 v[4:5], v[6:7], 0, s[94:95]
	v_lshl_add_u64 v[4:5], v[4:5], 0, v[118:119]
	v_lshlrev_b32_e32 v0, 6, v0
	global_load_dword v238, v[4:5], off
	global_load_dword v237, v[4:5], off offset:128
	global_load_dword v236, v[4:5], off offset:1024
	global_load_dword v235, v[4:5], off offset:1152
	v_ashrrev_i32_e32 v1, 31, v0
	v_lshl_add_u64 v[0:1], v[0:1], 3, v[130:131]
	v_lshl_add_u64 v[4:5], v[6:7], 0, s[46:47]
	v_lshl_add_u64 v[68:69], v[4:5], 0, v[122:123]
	global_load_dwordx4 v[4:7], v[0:1], off
	global_load_dwordx3 v[108:110], v[68:69], off offset:2048
	s_and_saveexec_b64 s[2:3], s[4:5]
	s_movk_i32 s33, 0x600
	s_cbranch_execz .LBB0_601
; __device__ __forceinline__ unsigned pk2(float lo, float hi) { f32x2_t v = {lo, hi}; bf16x2_t b = __builtin_convertvector(v, bf16x2_t); return __builtin_bit_cast(unsigned, b); }
; __device__ __forceinline__ float lo_bf(unsigned u) { return __uint_as_float(u << 16); }
; __device__ __forceinline__ float hi_bf(unsigned u) { return __uint_as_float(u & 0xffff0000u); }
; template <int MODE>
; __device__ void scan_unit(int swave, const Params& p, int j, int b, int h, int dir, char* shm) {
;     ...
;   auto ostore = [&](int c, const bf16_t* obuf) {
;     for (int idx = tid; idx < 16 * DV / 4; idx += 512) {
;       const int i = idx / (DV / 4), cc = (idx % (DV / 4)) * 4;
;       uint2 o = *(const uint2*)(obuf + i * OS + cc);
;       if (KS == 2) {
;         const uint2 o2 = *(const uint2*)(obuf + (16 + i) * OS + cc);
;         o.x = pk2(lo_bf(o.x) + lo_bf(o2.x), hi_bf(o.x) + hi_bf(o2.x)); o.y = pk2(lo_bf(o.y) + lo_bf(o2.y), hi_bf(o.y) + hi_bf(o2.y));
;       }
;       *(uint2*)(O + (rowbase + tokof(c, i)) * OLD + cc) = o;
;     }
	s_sub_i32 s34, 0x7f0, s25
	s_cmp_lg_u64 s[0:1], 0
	s_cselect_b32 s34, s25, s34
	s_add_i32 s34, s34, s18
	s_mul_i32 s35, s34, 0x600
	s_add_u32 s28, s42, s35
	s_addc_u32 s29, s43, 0
	v_add_u32_e32 v2, v225, v243
	v_add_u32_e32 v78, v225, v244
	ds_read_b64 v[70:71], v2
	ds_read_b64 v[72:73], v2 offset:6272
	ds_read_b64 v[0:1], v78
	ds_read_b64 v[68:69], v78 offset:6272
	s_waitcnt lgkmcnt(2)
	v_lshlrev_b32_e32 v74, 16, v70
	v_lshlrev_b32_e32 v76, 16, v72
	v_and_b32_e32 v75, 0xffff0000, v70
	v_and_b32_e32 v77, 0xffff0000, v72
	v_pk_add_f32 v[74:75], v[74:75], v[76:77]
	v_lshlrev_b32_e32 v76, 16, v73
	v_and_b32_e32 v77, 0xffff0000, v73
	v_cvt_pk_bf16_f32 v70, v74, v75
	v_lshlrev_b32_e32 v74, 16, v71
	v_and_b32_e32 v75, 0xffff0000, v71
	v_pk_add_f32 v[74:75], v[74:75], v[76:77]
	s_nop 0
	v_cvt_pk_bf16_f32 v71, v74, v75
	s_nop 0
	global_store_dwordx2 v249, v[70:71], s[28:29]
	v_cmp_gt_u32_e32 vcc, 0x100, v111
	s_and_saveexec_b64 s[34:35], vcc
	s_cbranch_execz .Lros_skip_c
	s_waitcnt lgkmcnt(0)
	v_lshlrev_b32_e32 v74, 16, v0
	v_lshlrev_b32_e32 v76, 16, v68
	v_and_b32_e32 v75, 0xffff0000, v0
	v_and_b32_e32 v77, 0xffff0000, v68
	v_pk_add_f32 v[74:75], v[74:75], v[76:77]
	v_lshlrev_b32_e32 v76, 16, v69
	v_and_b32_e32 v77, 0xffff0000, v69
	v_cvt_pk_bf16_f32 v0, v74, v75
	v_lshlrev_b32_e32 v74, 16, v1
	v_and_b32_e32 v75, 0xffff0000, v1
	v_pk_add_f32 v[74:75], v[74:75], v[76:77]
	s_nop 0
	v_cvt_pk_bf16_f32 v1, v74, v75
	s_nop 0
	global_store_dwordx2 v250, v[0:1], s[28:29]
.Lros_skip_c:
	s_or_b64 exec, exec, s[34:35]
	s_waitcnt lgkmcnt(0)
	s_or_b32 s20, s25, 16
	s_sub_i32 s34, 0x7f0, s20
	s_cmp_lg_u64 s[0:1], 0
	s_cselect_b32 s34, s20, s34
	s_add_i32 s34, s34, s18
	s_mul_i32 s35, s34, 0x600
	s_add_u32 s28, s42, s35
	s_addc_u32 s29, s43, 0
	v_add_u32_e32 v2, v226, v243
	v_add_u32_e32 v78, v226, v244
	ds_read_b64 v[70:71], v2
	ds_read_b64 v[72:73], v2 offset:6272
	ds_read_b64 v[0:1], v78
	ds_read_b64 v[68:69], v78 offset:6272
	s_waitcnt lgkmcnt(2)
	v_lshlrev_b32_e32 v74, 16, v70
	v_lshlrev_b32_e32 v76, 16, v72
	v_and_b32_e32 v75, 0xffff0000, v70
	v_and_b32_e32 v77, 0xffff0000, v72
	v_pk_add_f32 v[74:75], v[74:75], v[76:77]
	v_lshlrev_b32_e32 v76, 16, v73
	v_and_b32_e32 v77, 0xffff0000, v73
	v_cvt_pk_bf16_f32 v70, v74, v75
	v_lshlrev_b32_e32 v74, 16, v71
	v_and_b32_e32 v75, 0xffff0000, v71
	v_pk_add_f32 v[74:75], v[74:75], v[76:77]
	s_nop 0
	v_cvt_pk_bf16_f32 v71, v74, v75
	s_nop 0
	global_store_dwordx2 v249, v[70:71], s[28:29]
	v_cmp_gt_u32_e32 vcc, 0x100, v111
	s_and_saveexec_b64 s[34:35], vcc
	s_cbranch_execz .Lros_skip_d
	s_waitcnt lgkmcnt(0)
	v_lshlrev_b32_e32 v74, 16, v0
	v_lshlrev_b32_e32 v76, 16, v68
	v_and_b32_e32 v75, 0xffff0000, v0
	v_and_b32_e32 v77, 0xffff0000, v68
	v_pk_add_f32 v[74:75], v[74:75], v[76:77]
	v_lshlrev_b32_e32 v76, 16, v69
	v_and_b32_e32 v77, 0xffff0000, v69
	v_cvt_pk_bf16_f32 v0, v74, v75
	v_lshlrev_b32_e32 v74, 16, v1
	v_and_b32_e32 v75, 0xffff0000, v1
	v_pk_add_f32 v[74:75], v[74:75], v[76:77]
	s_nop 0
	v_cvt_pk_bf16_f32 v1, v74, v75
	s_nop 0
	global_store_dwordx2 v250, v[0:1], s[28:29]
.Lros_skip_d:
	s_or_b64 exec, exec, s[34:35]
	s_waitcnt lgkmcnt(0)
; template <int MODE>
; __device__ void scan_unit(int swave, const Params& p, int j, int b, int h, int dir, char* shm) {
;     ...
;       const float KSC = 0.08838834764831845f;
;       const float qx0 = lo_bf(R.q), qx1 = hi_bf(R.q), qy0 = lo_bf(R.q2), qy1 = hi_bf(R.q2);
;       const float kx0 = lo_bf(R.k) * KSC, kx1 = hi_bf(R.k) * KSC, ky0 = lo_bf(R.k2) * KSC, ky1 = hi_bf(R.k2) * KSC;
;       const float c0 = R.cs.x, sn0 = R.cs.y, c1 = R.cs.z, sn1 = R.cs.w;
;       const float qa0 = qx0 * c0 - qy0 * sn0, qb0 = qx0 * sn0 + qy0 * c0, qa1 = qx1 * c1 - qy1 * sn1, qb1 = qx1 * sn1 + qy1 * c1;
;       const float ka0 = kx0 * c0 - ky0 * sn0, kb0 = kx0 * sn0 + ky0 * c0, ka1 = kx1 * c1 - ky1 * sn1, kb1 = kx1 * sn1 + ky1 * c1;
;       const float ein = ret_ein, eti = ret_eti, eout = ret_eout;
;       *(unsigned*)(qin + ti * QS + dp) = pk2(qa0 * ein, qa1 * ein); *(unsigned*)(qin + ti * QS + 64 + dp) = pk2(qb0 * ein, qb1 * ein);
;       *(unsigned*)(ktil + ti * QS + dp) = pk2(ka0 * eti, ka1 * eti); *(unsigned*)(ktil + ti * QS + 64 + dp) = pk2(kb0 * eti, kb1 * eti);
;       koutT[dp * 16 + ti] = f2bf(ka0 * eout); koutT[(dp + 1) * 16 + ti] = f2bf(ka1 * eout);
;       koutT[(64 + dp) * 16 + ti] = f2bf(kb0 * eout); koutT[(65 + dp) * 16 + ti] = f2bf(kb1 * eout);
;       if (ti == 0) { const float dd = ret_dd; *(float2*)(dec + dp) = make_float2(dd, dd); *(float2*)(dec + 64 + dp) = make_float2(dd, dd); }
;       const int c6 = vg * 6;
;       vT[(c6 + 0) * VS + ti] = (bf16_t)(R.v30 & 0xffff); vT[(c6 + 1) * VS + ti] = (bf16_t)(R.v30 >> 16);
;       vT[(c6 + 2) * VS + ti] = (bf16_t)(R.v31 & 0xffff); vT[(c6 + 3) * VS + ti] = (bf16_t)(R.v31 >> 16);
;       vT[(c6 + 4) * VS + ti] = (bf16_t)(R.v32 & 0xffff); vT[(c6 + 5) * VS + ti] = (bf16_t)(R.v32 >> 16);
;     }
;   };
;   f32x4 S[4][NVT];
; #pragma unroll
;   for (int a = 0; a < 4; ++a)
; #pragma unroll
;     for (int t = 0; t < NVT; ++t) S[a][t] = (f32x4){0.f, 0.f, 0.f, 0.f};
;   auto compute = [&](const char* buf, bf16_t* obuf) {
;     const bf16_t* qin = (const bf16_t*)buf; const bf16_t* ktil = (const bf16_t*)(buf + OFF_KT); const bf16_t* koutT = (const bf16_t*)(buf + OFF_KO);
;     const bf16_t* vT = (const bf16_t*)(buf + OFF_VT); const float* dec = (const float*)(buf + OFF_DEC);
;     bf16x8 Asc = {0, 0, 0, 0, 0, 0, 0, 0};
;     if (KS == 1 || wk == 0) {
;       f32x4 sc = {0.f, 0.f, 0.f, 0.f};
; #pragma unroll
.LBB0_601:
	s_or_b64 exec, exec, s[2:3]
	v_lshlrev_b32_e32 v68, 16, v106
	v_and_b32_e32 v69, 0xffff0000, v106
	v_mov_b32_e32 v75, v18
	v_mov_b32_e32 v18, v17
	v_lshlrev_b32_e32 v0, 16, v107
	v_and_b32_e32 v1, 0xffff0000, v107
	v_mov_b32_e32 v74, v16
	v_pk_mul_f32 v[16:17], v[18:19], v[68:69]
	v_lshlrev_b32_e32 v72, 16, v104
	v_pk_fma_f32 v[16:17], v[74:75], v[0:1], v[16:17] neg_lo:[0,0,1] neg_hi:[0,0,1]
	v_pk_mul_f32 v[0:1], v[18:19], v[0:1]
	v_and_b32_e32 v73, 0xffff0000, v104
	v_pk_fma_f32 v[0:1], v[74:75], v[68:69], v[0:1]
	v_pk_mul_f32 v[16:17], v[124:125], v[16:17]
	v_pk_mul_f32 v[0:1], v[124:125], v[0:1]
	s_mov_b32 s2, 0x3db504f3
	v_lshlrev_b32_e32 v70, 16, v105
	v_and_b32_e32 v71, 0xffff0000, v105
	v_cvt_pk_bf16_f32 v2, v16, v17
	v_cvt_pk_bf16_f32 v0, v0, v1
	v_pk_mul_f32 v[16:17], v[72:73], s[2:3] op_sel_hi:[1,0]
	ds_write2_b32 v121, v2, v0 offset1:32
	v_pk_mul_f32 v[0:1], v[70:71], s[2:3] op_sel_hi:[1,0]
	v_pk_mul_f32 v[68:69], v[18:19], v[16:17]
	s_nop 0
	v_pk_fma_f32 v[68:69], v[74:75], v[0:1], v[68:69] neg_lo:[0,0,1] neg_hi:[0,0,1]
	v_pk_mul_f32 v[0:1], v[0:1], v[18:19]
	v_pk_mul_f32 v[70:71], v[126:127], v[68:69]
	v_pk_fma_f32 v[0:1], v[16:17], v[74:75], v[0:1]
	v_cvt_pk_bf16_f32 v2, v70, v71
	v_pk_mul_f32 v[16:17], v[126:127], v[0:1]
	v_mul_f32_e32 v0, v117, v0
	v_cvt_pk_bf16_f32 v16, v16, v17
	ds_write2_b32 v135, v2, v16 offset0:64 offset1:96
	v_mul_f32_e32 v2, v117, v68
	v_cvt_pk_bf16_f32 v2, v2, s0
	v_cvt_pk_bf16_f32 v0, v0, s0
	ds_write_b16 v136, v2 offset:8704
	v_mul_f32_e32 v2, v117, v69
	ds_write_b16 v136, v0 offset:10752
	v_mul_f32_e32 v0, v117, v1
	v_cvt_pk_bf16_f32 v2, v2, s0
	v_cvt_pk_bf16_f32 v0, v0, s0
	ds_write_b16 v136, v2 offset:8736
	ds_write_b16 v136, v0 offset:10784
	s_and_saveexec_b64 s[2:3], s[16:17]
	v_add_u32_e32 v0, 0x5000, v141
	ds_write2_b64 v0, v[128:129], v[128:129] offset1:32
	s_or_b64 exec, exec, s[2:3]
	v_lshlrev_b32_e32 v16, 16, v102
	v_and_b32_e32 v17, 0xffff0000, v102
	v_mov_b32_e32 v71, v14
	v_mov_b32_e32 v14, v13
	v_lshlrev_b32_e32 v0, 16, v103
	v_and_b32_e32 v1, 0xffff0000, v103
	v_mov_b32_e32 v70, v12
	v_pk_mul_f32 v[12:13], v[14:15], v[16:17]
	v_lshlrev_b32_e32 v68, 16, v97
	v_pk_fma_f32 v[12:13], v[70:71], v[0:1], v[12:13] neg_lo:[0,0,1] neg_hi:[0,0,1]
	v_pk_mul_f32 v[0:1], v[14:15], v[0:1]
	v_and_b32_e32 v69, 0xffff0000, v97
	v_pk_fma_f32 v[0:1], v[70:71], v[16:17], v[0:1]
	v_pk_mul_f32 v[12:13], v[124:125], v[12:13]
	v_pk_mul_f32 v[0:1], v[124:125], v[0:1]
	s_mov_b32 s2, 0x3db504f3
	v_lshlrev_b32_e32 v18, 16, v101
	v_and_b32_e32 v19, 0xffff0000, v101
	v_cvt_pk_bf16_f32 v2, v12, v13
	v_cvt_pk_bf16_f32 v0, v0, v1
	v_pk_mul_f32 v[12:13], v[68:69], s[2:3] op_sel_hi:[1,0]
	ds_write_b16 v137, v98 offset:12800
	ds_write_b16_d16_hi v137, v98 offset:12840
	ds_write_b16 v137, v99 offset:12880
	ds_write_b16_d16_hi v137, v99 offset:12920
	ds_write_b16 v137, v100 offset:12960
	ds_write_b16_d16_hi v137, v100 offset:13000
	ds_write2_b32 v139, v2, v0 offset0:128 offset1:160
	v_pk_mul_f32 v[0:1], v[18:19], s[2:3] op_sel_hi:[1,0]
	v_pk_mul_f32 v[16:17], v[14:15], v[12:13]
	s_nop 0
	v_pk_fma_f32 v[16:17], v[70:71], v[0:1], v[16:17] neg_lo:[0,0,1] neg_hi:[0,0,1]
	v_pk_mul_f32 v[0:1], v[0:1], v[14:15]
	v_pk_mul_f32 v[18:19], v[126:127], v[16:17]
	v_pk_fma_f32 v[0:1], v[12:13], v[70:71], v[0:1]
	v_cvt_pk_bf16_f32 v2, v18, v19
	v_pk_mul_f32 v[12:13], v[126:127], v[0:1]
	v_mul_f32_e32 v0, v117, v0
	v_cvt_pk_bf16_f32 v12, v12, v13
	ds_write2_b32 v140, v2, v12 offset0:192 offset1:224
	v_mul_f32_e32 v2, v117, v16
	v_cvt_pk_bf16_f32 v2, v2, s0
	v_cvt_pk_bf16_f32 v0, v0, s0
	ds_write_b16 v136, v2 offset:29696
	v_mul_f32_e32 v2, v117, v17
	ds_write_b16 v136, v0 offset:31744
	v_mul_f32_e32 v0, v117, v1
	v_cvt_pk_bf16_f32 v2, v2, s0
	v_cvt_pk_bf16_f32 v0, v0, s0
	ds_write_b16 v136, v2 offset:29728
	ds_write_b16 v136, v0 offset:31776
	s_and_saveexec_b64 s[2:3], s[16:17]
	v_add_u32_e32 v0, 0xa000, v141
	ds_write2_b64 v0, v[128:129], v[128:129] offset0:64 offset1:96
	s_or_b64 exec, exec, s[2:3]
	v_mov_b32_e32 v12, 0
	v_mov_b32_e32 v68, 0
	v_mov_b32_e32 v69, 0
	v_mov_b32_e32 v70, 0
	v_mov_b32_e32 v71, 0
	ds_write_b16 v137, v94 offset:33792
	ds_write_b16_d16_hi v137, v94 offset:33832
	ds_write_b16 v137, v95 offset:33872
	ds_write_b16_d16_hi v137, v95 offset:33912
	ds_write_b16 v137, v96 offset:33952
	ds_write_b16_d16_hi v137, v96 offset:33992
	s_and_saveexec_b64 s[2:3], s[6:7]
	s_cbranch_execz .LBB0_607
	ds_read_b128 v[14:17], v160 offset:46336
	ds_read_b128 v[68:71], v160 offset:41984
	ds_read_b128 v[76:79], v160 offset:46400
	ds_read_b128 v[80:83], v160 offset:42048
	ds_read_b128 v[72:75], v160 offset:46464
	s_pack_ll_b32_b16 s20, 0, 0
	s_waitcnt lgkmcnt(3)
	v_mfma_f32_16x16x32_bf16 v[14:17], v[14:17], v[68:71], 0
	ds_read_b128 v[68:71], v160 offset:42112
	s_waitcnt lgkmcnt(2)
	v_mfma_f32_16x16x32_bf16 v[14:17], v[76:79], v[80:83], v[14:17]
	ds_read_b128 v[76:79], v160 offset:46528
	ds_read_b128 v[80:83], v160 offset:42176
	s_waitcnt lgkmcnt(2)
	v_mfma_f32_16x16x32_bf16 v[14:17], v[72:75], v[68:71], v[14:17]
	s_waitcnt lgkmcnt(0)
	v_mfma_f32_16x16x32_bf16 v[14:17], v[76:79], v[80:83], v[14:17]
	v_mov_b32_e32 v70, s20
	v_mov_b32_e32 v71, s20
	s_nop 5
	v_cndmask_b32_e64 v0, v14, 0, s[8:9]
	v_cndmask_b32_e64 v1, 0, v15, s[10:11]
	v_cvt_pk_bf16_f32 v68, v0, v1
	v_cndmask_b32_e64 v0, v16, 0, s[12:13]
	v_cndmask_b32_e64 v1, v17, 0, s[14:15]
	v_cvt_pk_bf16_f32 v69, v0, v1

; __global__ void __launch_bounds__(512, 2) mega(Params p, int ph_lo, int ph_hi) {
	.amdhsa_kernel _Z4mega6Paramsii
		.amdhsa_group_segment_fixed_size 0
		.amdhsa_private_segment_fixed_size 0
		.amdhsa_kernarg_size 504
		.amdhsa_user_sgpr_count 2
		.amdhsa_user_sgpr_dispatch_ptr 0
		.amdhsa_user_sgpr_queue_ptr 0
		.amdhsa_user_sgpr_kernarg_segment_ptr 1
		.amdhsa_user_sgpr_dispatch_id 0
		.amdhsa_user_sgpr_kernarg_preload_length 0
		.amdhsa_user_sgpr_kernarg_preload_offset 0
		.amdhsa_user_sgpr_private_segment_size 0
		.amdhsa_uses_dynamic_stack 0
		.amdhsa_enable_private_segment 0
		.amdhsa_system_sgpr_workgroup_id_x 1
		.amdhsa_system_sgpr_workgroup_id_y 0
		.amdhsa_system_sgpr_workgroup_id_z 0
		.amdhsa_system_sgpr_workgroup_info 0
		.amdhsa_system_vgpr_workitem_id 2
		.amdhsa_next_free_vgpr 252
		.amdhsa_next_free_sgpr 98
		.amdhsa_accum_offset 252
		.amdhsa_reserve_vcc 1
		.amdhsa_float_round_mode_32 0
		.amdhsa_float_round_mode_16_64 0
		.amdhsa_float_denorm_mode_32 3
		.amdhsa_float_denorm_mode_16_64 3
		.amdhsa_dx10_clamp 1
		.amdhsa_ieee_mode 1
		.amdhsa_fp16_overflow 0
		.amdhsa_tg_split 0
		.amdhsa_exception_fp_ieee_invalid_op 0
		.amdhsa_exception_fp_denorm_src 0
		.amdhsa_exception_fp_ieee_div_zero 0
		.amdhsa_exception_fp_ieee_overflow 0
		.amdhsa_exception_fp_ieee_underflow 0
		.amdhsa_exception_fp_ieee_inexact 0
		.amdhsa_exception_int_div_zero 0
	.end_amdhsa_kernel

; __global__ void __launch_bounds__(512, 2) mega(Params p, int ph_lo, int ph_hi) {
amdhsa.kernels:
  - .agpr_count:     0
    .args:
      - .offset:         0
        .size:           240
        .value_kind:     by_value
      - .offset:         240
        .size:           4
        .value_kind:     by_value
      - .offset:         244
        .size:           4
        .value_kind:     by_value
      - .offset:         248
        .size:           4
        .value_kind:     hidden_block_count_x
      - .offset:         252
        .size:           4
        .value_kind:     hidden_block_count_y
      - .offset:         256
        .size:           4
        .value_kind:     hidden_block_count_z
      - .offset:         260
        .size:           2
        .value_kind:     hidden_group_size_x
      - .offset:         262
        .size:           2
        .value_kind:     hidden_group_size_y
      - .offset:         264
        .size:           2
        .value_kind:     hidden_group_size_z
      - .offset:         266
        .size:           2
        .value_kind:     hidden_remainder_x
      - .offset:         268
        .size:           2
        .value_kind:     hidden_remainder_y
      - .offset:         270
        .size:           2
        .value_kind:     hidden_remainder_z
      - .offset:         288
        .size:           8
        .value_kind:     hidden_global_offset_x
      - .offset:         296
        .size:           8
        .value_kind:     hidden_global_offset_y
      - .offset:         304
        .size:           8
        .value_kind:     hidden_global_offset_z
      - .offset:         312
        .size:           2
        .value_kind:     hidden_grid_dims
      - .offset:         336
        .size:           8
        .value_kind:     hidden_multigrid_sync_arg
      - .offset:         368
        .size:           4
        .value_kind:     hidden_dynamic_lds_size
    .group_segment_fixed_size: 0
    .kernarg_segment_align: 8
    .kernarg_segment_size: 504
    .language:       OpenCL C
    .language_version:
      - 2
      - 0
    .max_flat_workgroup_size: 512
    .name:           _Z4mega6Paramsii
    .private_segment_fixed_size: 0
    .sgpr_count:     104
    .sgpr_spill_count: 260
    .symbol:         _Z4mega6Paramsii.kd
    .uniform_work_group_size: 1
    .uses_dynamic_stack: false
    .vgpr_count:     252
    .vgpr_spill_count: 0
    .wavefront_size: 64
